# plusH3
# baseline (speedup 1.0000x reference)
; #define PG8_STAGE(bufoff, gbase, voff) do { _Pragma("unroll") for (int _i = 0; _i < 2; ++_i) \
;         __builtin_amdgcn_global_load_lds((const unsigned*)((const char*)(gbase) + (voff)[_i]), (PG8_LAS unsigned*)(lds + (bufoff) + ldsw + _i * 8192), 16, 0, 0); } while (0)
; #define PG8_LDA(dst, b, h) do { _Pragma("unroll") for (int m = 0; m < 4; ++m) _Pragma("unroll") for (int k = 0; k < 2; ++k) dst[m][k] = *(const PG8_LAS bf16x8*)(lds + PG8_SA(b, h) + aoff + m * 2048 + k * 1024); } while (0)
; #define PG8_LDB(dst, b, h) do { _Pragma("unroll") for (int n = 0; n < 2; ++n) _Pragma("unroll") for (int k = 0; k < 2; ++k) dst[n][k] = *(const PG8_LAS bf16x8*)(lds + PG8_SB(b, h) + boff + n * 2048 + k * 1024); } while (0)
; #define PG8_MMA(ai, bj, At, Bt) do { __builtin_amdgcn_s_setprio(1); _Pragma("unroll") for (int m = 0; m < 4; ++m) _Pragma("unroll") for (int n = 0; n < 2; ++n) _Pragma("unroll") for (int k = 0; k < 2; ++k) \
;         acc[ai][bj][m][n] = __builtin_amdgcn_mfma_f32_16x16x32_bf16(Bt[n][k], At[m][k], acc[ai][bj][m][n], 0, 0, 0); __builtin_amdgcn_s_setprio(0); } while (0)
; #define PG8_WAIT_V(n) asm volatile("s_waitcnt vmcnt(" #n ")" ::: "memory")
; #define PG8_BAR __builtin_amdgcn_s_barrier()
; template <class Epi, class Sched, bool ALIGN_EPI = false, bool SP2 = false, bool DUAL = false>
; __device__ __forceinline__ void gemm_phase(PG8_LAS unsigned char* lds, const Gemm g, const Sched& S, const Epi& E) {
;     ...
;         for (int t = 0; t < nt; t += 2) {
;             const bool last = (t == nt - 2);
;             const char* a1 = cA + (size_t)(t + 1) * kstep;
;             const char* a2 = last ? nA : cA + (size_t)(t + 2) * kstep; const char* b2 = last ? nB : cB + (size_t)(t + 2) * kstep;
;             const char* a3 = a2 + kstep; const char* b3 = b2 + kstep;
;             if (last && has_next) S.a_ready(nxt);
;             if constexpr (SP2) {
;             PG8_LDB(B0, 0, 0); PG8_LDB(B1, 0, 1); PG8_SCHED; PG8_LDA(At, 0, 0); PG8_STAGE(PG8_SA(1, 1), a1 + hstep, voffA);
;             PG8_WAIT_V(8); PG8_WAIT_L(0); PG8_BAR; PG8_MMA(0, 0, At, B0); PG8_MMA(0, 1, At, B1); PG8_BAR; PG8_SCHED;
;             PG8_LDA(At, 0, 1); PG8_STAGE(PG8_SB(0, 0), b2, voffB); PG8_STAGE(PG8_SB(0, 1), b2 + hstep, voffB); PG8_STAGE(PG8_SA(0, 0), a2, voffA);
;             PG8_WAIT_V(8); PG8_WAIT_L(0); PG8_BAR; PG8_MMA(1, 0, At, B0); PG8_MMA(1, 1, At, B1); PG8_BAR; PG8_SCHED;
.LBB0_251:
	s_ashr_i32 s87, s86, 31
	s_lshl_b64 s[16:17], s[86:87], 20
	s_add_u32 s92, s58, s16
	s_addc_u32 s93, s59, s17
	s_and_b64 s[16:17], s[4:5], exec
	s_cselect_b32 s7, s93, s11
	s_cselect_b32 s9, s92, s10
	s_ashr_i32 s1, s0, 31
	s_lshl_b64 s[16:17], s[0:1], 20
	s_add_u32 s88, s90, s16
	s_addc_u32 s89, s91, s17
	s_and_b64 s[16:17], s[4:5], exec
	s_cselect_b32 s1, s89, s15
	s_cselect_b32 s45, s88, s14
	s_add_u32 s10, s10, 0x80080
	s_addc_u32 s11, s11, 0
	s_add_u32 s46, s14, 0x100
	s_addc_u32 s47, s15, 0
	s_mov_b32 s48, -2
	s_add_u32 s14, s10, 0xfff80080
	s_addc_u32 s15, s11, -1
	s_cmp_eq_u32 s48, 28
	s_cselect_b32 s17, s7, s15
	s_cselect_b32 s16, s9, s14
	s_cselect_b32 s15, s1, s47
	s_cselect_b32 s14, s45, s46
	s_waitcnt vmcnt(8)
	s_waitcnt lgkmcnt(0)
	s_setprio 1
	s_barrier
	v_mfma_f32_16x16x32_bf16 v[140:143], v[80:83], v[208:211], 0
	v_mfma_f32_16x16x32_bf16 v[132:135], v[88:91], v[208:211], 0
	v_mfma_f32_16x16x32_bf16 v[124:127], v[80:83], v[216:219], 0
	v_mfma_f32_16x16x32_bf16 v[120:123], v[88:91], v[216:219], 0
	v_mfma_f32_16x16x32_bf16 v[108:111], v[80:83], v[232:235], 0
	v_mfma_f32_16x16x32_bf16 v[104:107], v[88:91], v[232:235], 0
	v_mfma_f32_16x16x32_bf16 v[76:79], v[80:83], v[240:243], 0
	v_mfma_f32_16x16x32_bf16 v[72:75], v[88:91], v[240:243], 0
	v_mfma_f32_16x16x32_bf16 v[140:143], v[84:87], v[212:215], v[140:143]
	v_mfma_f32_16x16x32_bf16 v[132:135], v[92:95], v[212:215], v[132:135]
	v_mfma_f32_16x16x32_bf16 v[124:127], v[84:87], v[220:223], v[124:127]
	v_mfma_f32_16x16x32_bf16 v[120:123], v[92:95], v[220:223], v[120:123]
	v_mfma_f32_16x16x32_bf16 v[108:111], v[84:87], v[236:239], v[108:111]
	v_mfma_f32_16x16x32_bf16 v[104:107], v[92:95], v[236:239], v[104:107]
	v_mfma_f32_16x16x32_bf16 v[76:79], v[84:87], v[244:247], v[76:79]
	v_mfma_f32_16x16x32_bf16 v[72:75], v[92:95], v[244:247], v[72:75]
	s_setprio 0
	s_setprio 1
	v_mfma_f32_16x16x32_bf16 v[136:139], v[144:147], v[208:211], 0
	v_mfma_f32_16x16x32_bf16 v[128:131], v[152:155], v[208:211], 0
	v_mfma_f32_16x16x32_bf16 v[116:119], v[144:147], v[216:219], 0
	v_mfma_f32_16x16x32_bf16 v[112:115], v[152:155], v[216:219], 0
	v_mfma_f32_16x16x32_bf16 v[100:103], v[144:147], v[232:235], 0
	v_mfma_f32_16x16x32_bf16 v[96:99], v[152:155], v[232:235], 0
	v_mfma_f32_16x16x32_bf16 v[68:71], v[144:147], v[240:243], 0
	v_mfma_f32_16x16x32_bf16 v[64:67], v[152:155], v[240:243], 0
	v_mfma_f32_16x16x32_bf16 v[136:139], v[148:151], v[212:215], v[136:139]
	v_mfma_f32_16x16x32_bf16 v[128:131], v[156:159], v[212:215], v[128:131]
	v_mfma_f32_16x16x32_bf16 v[116:119], v[148:151], v[220:223], v[116:119]
	v_mfma_f32_16x16x32_bf16 v[112:115], v[156:159], v[220:223], v[112:115]
	v_mfma_f32_16x16x32_bf16 v[100:103], v[148:151], v[236:239], v[100:103]
	v_mfma_f32_16x16x32_bf16 v[96:99], v[156:159], v[236:239], v[96:99]
	v_mfma_f32_16x16x32_bf16 v[68:71], v[148:151], v[244:247], v[68:71]
	v_mfma_f32_16x16x32_bf16 v[64:67], v[156:159], v[244:247], v[64:67]
	s_barrier
	s_setprio 0
	v_lshl_add_u64 v[192:193], s[10:11], 0, v[186:187]
	s_add_i32 m0, s19, 0xc000
	s_nop 0
	global_load_lds_dwordx4 v[192:193], off
	v_lshl_add_u64 v[192:193], s[10:11], 0, v[188:189]
	s_add_i32 m0, s19, 0xe000
	s_nop 0
	global_load_lds_dwordx4 v[192:193], off
	s_add_i32 s49, s31, s18
	v_lshl_add_u64 v[192:193], s[14:15], 0, v[166:167]
	s_mov_b32 m0, s49
	ds_read_b128 v[208:211], v203 offset:16384
	ds_read_b128 v[212:215], v203 offset:17408
	ds_read_b128 v[216:219], v203 offset:18432
	ds_read_b128 v[220:223], v203 offset:19456
	ds_read_b128 v[232:235], v203 offset:20480
	ds_read_b128 v[236:239], v203 offset:21504
	ds_read_b128 v[240:243], v203 offset:22528
	ds_read_b128 v[244:247], v203 offset:23552
	global_load_lds_dwordx4 v[192:193], off
	s_add_i32 m0, s49, 0x2000
	s_add_u32 s50, s14, 0x80000
	v_lshl_add_u64 v[248:249], s[14:15], 0, v[170:171]
	s_addc_u32 s51, s15, 0
	s_add_i32 s49, s34, s18
	global_load_lds_dwordx4 v[248:249], off
	v_lshl_add_u64 v[250:251], s[50:51], 0, v[166:167]
	s_mov_b32 m0, s49
	v_lshl_add_u64 v[252:253], s[16:17], 0, v[168:169]
	global_load_lds_dwordx4 v[250:251], off
	v_lshl_add_u64 v[250:251], s[50:51], 0, v[170:171]
	s_add_i32 m0, s49, 0x2000
	s_nop 0
	global_load_lds_dwordx4 v[250:251], off
	v_lshl_add_u64 v[250:251], s[16:17], 0, v[164:165]
	s_mov_b32 m0, s19
	s_nop 0
	global_load_lds_dwordx4 v[250:251], off
	s_mov_b32 m0, s20
	s_nop 0
	global_load_lds_dwordx4 v[252:253], off
	s_waitcnt vmcnt(8)
	s_waitcnt lgkmcnt(0)
	s_setprio 1
	s_barrier
	v_mfma_f32_16x16x32_bf16 v[60:63], v[80:83], v[208:211], 0
	v_mfma_f32_16x16x32_bf16 v[56:59], v[88:91], v[208:211], 0
	v_mfma_f32_16x16x32_bf16 v[44:47], v[80:83], v[216:219], 0
	v_mfma_f32_16x16x32_bf16 v[40:43], v[88:91], v[216:219], 0
	v_mfma_f32_16x16x32_bf16 v[28:31], v[80:83], v[232:235], 0
	v_mfma_f32_16x16x32_bf16 v[24:27], v[88:91], v[232:235], 0
	v_mfma_f32_16x16x32_bf16 v[12:15], v[80:83], v[240:243], 0
	v_mfma_f32_16x16x32_bf16 v[8:11], v[88:91], v[240:243], 0
	v_mfma_f32_16x16x32_bf16 v[60:63], v[84:87], v[212:215], v[60:63]
	v_mfma_f32_16x16x32_bf16 v[56:59], v[92:95], v[212:215], v[56:59]
	v_mfma_f32_16x16x32_bf16 v[44:47], v[84:87], v[220:223], v[44:47]
	v_mfma_f32_16x16x32_bf16 v[40:43], v[92:95], v[220:223], v[40:43]
	v_mfma_f32_16x16x32_bf16 v[28:31], v[84:87], v[236:239], v[28:31]
	v_mfma_f32_16x16x32_bf16 v[24:27], v[92:95], v[236:239], v[24:27]
	v_mfma_f32_16x16x32_bf16 v[12:15], v[84:87], v[244:247], v[12:15]
	v_mfma_f32_16x16x32_bf16 v[8:11], v[92:95], v[244:247], v[8:11]
	s_setprio 0
	s_setprio 1
	v_mfma_f32_16x16x32_bf16 v[52:55], v[144:147], v[208:211], 0
	v_mfma_f32_16x16x32_bf16 v[48:51], v[152:155], v[208:211], 0
	v_mfma_f32_16x16x32_bf16 v[36:39], v[144:147], v[216:219], 0
	v_mfma_f32_16x16x32_bf16 v[32:35], v[152:155], v[216:219], 0
	v_mfma_f32_16x16x32_bf16 v[20:23], v[144:147], v[232:235], 0
	v_mfma_f32_16x16x32_bf16 v[16:19], v[152:155], v[232:235], 0
	v_mfma_f32_16x16x32_bf16 v[4:7], v[144:147], v[240:243], 0
	v_mfma_f32_16x16x32_bf16 v[0:3], v[152:155], v[240:243], 0
	v_mfma_f32_16x16x32_bf16 v[52:55], v[148:151], v[212:215], v[52:55]
	v_mfma_f32_16x16x32_bf16 v[48:51], v[156:159], v[212:215], v[48:51]
	v_mfma_f32_16x16x32_bf16 v[36:39], v[148:151], v[220:223], v[36:39]
	v_mfma_f32_16x16x32_bf16 v[32:35], v[156:159], v[220:223], v[32:35]
	v_mfma_f32_16x16x32_bf16 v[20:23], v[148:151], v[236:239], v[20:23]
	v_mfma_f32_16x16x32_bf16 v[16:19], v[156:159], v[236:239], v[16:19]
	v_mfma_f32_16x16x32_bf16 v[4:7], v[148:151], v[244:247], v[4:7]
	v_mfma_f32_16x16x32_bf16 v[0:3], v[156:159], v[244:247], v[0:3]
	s_barrier
; #define PG8_STAGE(bufoff, gbase, voff) do { _Pragma("unroll") for (int _i = 0; _i < 2; ++_i) \
;         __builtin_amdgcn_global_load_lds((const unsigned*)((const char*)(gbase) + (voff)[_i]), (PG8_LAS unsigned*)(lds + (bufoff) + ldsw + _i * 8192), 16, 0, 0); } while (0)
; #define PG8_LDA(dst, b, h) do { _Pragma("unroll") for (int m = 0; m < 4; ++m) _Pragma("unroll") for (int k = 0; k < 2; ++k) dst[m][k] = *(const PG8_LAS bf16x8*)(lds + PG8_SA(b, h) + aoff + m * 2048 + k * 1024); } while (0)
; #define PG8_LDB(dst, b, h) do { _Pragma("unroll") for (int n = 0; n < 2; ++n) _Pragma("unroll") for (int k = 0; k < 2; ++k) dst[n][k] = *(const PG8_LAS bf16x8*)(lds + PG8_SB(b, h) + boff + n * 2048 + k * 1024); } while (0)
; #define PG8_MMA(ai, bj, At, Bt) do { __builtin_amdgcn_s_setprio(1); _Pragma("unroll") for (int m = 0; m < 4; ++m) _Pragma("unroll") for (int n = 0; n < 2; ++n) _Pragma("unroll") for (int k = 0; k < 2; ++k) \
;         acc[ai][bj][m][n] = __builtin_amdgcn_mfma_f32_16x16x32_bf16(Bt[n][k], At[m][k], acc[ai][bj][m][n], 0, 0, 0); __builtin_amdgcn_s_setprio(0); } while (0)
; #define PG8_WAIT_V(n) asm volatile("s_waitcnt vmcnt(" #n ")" ::: "memory")
; #define PG8_WAIT_L(n) asm volatile("s_waitcnt lgkmcnt(" #n ")" ::: "memory")
; #define PG8_BAR __builtin_amdgcn_s_barrier()
; #define PG8_SCHED __builtin_amdgcn_sched_barrier(0)
; template <class Epi, class Sched, bool ALIGN_EPI = false, bool SP2 = false, bool DUAL = false>
; __device__ __forceinline__ void gemm_phase(PG8_LAS unsigned char* lds, const Gemm g, const Sched& S, const Epi& E) {
;     ...
;             PG8_LDB(B0, 1, 0); PG8_LDB(B1, 1, 1); PG8_SCHED; PG8_LDA(At, 1, 0); PG8_STAGE(PG8_SA(0, 1), a2 + hstep, voffA);
;             PG8_WAIT_V(8); PG8_WAIT_L(0); PG8_BAR; PG8_MMA(0, 0, At, B0); PG8_MMA(0, 1, At, B1); PG8_BAR; PG8_SCHED;
;             PG8_LDA(At, 1, 1); PG8_STAGE(PG8_SB(1, 0), b3, voffB); PG8_STAGE(PG8_SB(1, 1), b3 + hstep, voffB); PG8_STAGE(PG8_SA(1, 0), a3, voffA);
;             PG8_WAIT_V(8); PG8_WAIT_L(0); PG8_BAR; PG8_MMA(1, 0, At, B0); PG8_MMA(1, 1, At, B1); PG8_BAR; PG8_SCHED;
	s_setprio 0
	s_add_i32 s49, 0, 0x18000
	s_add_i32 s50, 0, 0x1c000
	v_add_u32_e32 v92, s49, v196
	v_add_u32_e32 v156, s50, v196
	ds_read_b128 v[80:83], v92
	ds_read_b128 v[84:87], v92 offset:1024
	ds_read_b128 v[88:91], v92 offset:2048
	ds_read_b128 v[92:95], v92 offset:3072
	ds_read_b128 v[144:147], v156
	ds_read_b128 v[148:151], v156 offset:1024
	ds_read_b128 v[152:155], v156 offset:2048
	ds_read_b128 v[156:159], v156 offset:3072
	s_add_u32 s16, s16, 0x80000
	s_addc_u32 s17, s17, 0
	s_mov_b32 m0, s21
	v_lshl_add_u64 v[228:229], s[16:17], 0, v[164:165]
	ds_read_b128 v[208:211], v203 offset:32768
	ds_read_b128 v[212:215], v203 offset:33792
	ds_read_b128 v[216:219], v203 offset:34816
	ds_read_b128 v[220:223], v203 offset:35840
	ds_read_b128 v[232:235], v203 offset:36864
	ds_read_b128 v[236:239], v203 offset:37888
	ds_read_b128 v[240:243], v203 offset:38912
	ds_read_b128 v[244:247], v203 offset:39936
	global_load_lds_dwordx4 v[228:229], off
	v_lshl_add_u64 v[228:229], s[16:17], 0, v[168:169]
	s_mov_b32 m0, s22
	s_nop 0
	global_load_lds_dwordx4 v[228:229], off
	s_waitcnt vmcnt(8)
	s_waitcnt lgkmcnt(0)
	s_setprio 1
	s_barrier
	v_mfma_f32_16x16x32_bf16 v[140:143], v[80:83], v[208:211], v[140:143]
	v_mfma_f32_16x16x32_bf16 v[132:135], v[88:91], v[208:211], v[132:135]
	v_mfma_f32_16x16x32_bf16 v[124:127], v[80:83], v[216:219], v[124:127]
	v_mfma_f32_16x16x32_bf16 v[120:123], v[88:91], v[216:219], v[120:123]
	v_mfma_f32_16x16x32_bf16 v[108:111], v[80:83], v[232:235], v[108:111]
	v_mfma_f32_16x16x32_bf16 v[104:107], v[88:91], v[232:235], v[104:107]
	v_mfma_f32_16x16x32_bf16 v[76:79], v[80:83], v[240:243], v[76:79]
	v_mfma_f32_16x16x32_bf16 v[72:75], v[88:91], v[240:243], v[72:75]
	v_mfma_f32_16x16x32_bf16 v[140:143], v[84:87], v[212:215], v[140:143]
	v_mfma_f32_16x16x32_bf16 v[132:135], v[92:95], v[212:215], v[132:135]
	v_mfma_f32_16x16x32_bf16 v[124:127], v[84:87], v[220:223], v[124:127]
	v_mfma_f32_16x16x32_bf16 v[120:123], v[92:95], v[220:223], v[120:123]
	v_mfma_f32_16x16x32_bf16 v[108:111], v[84:87], v[236:239], v[108:111]
	v_mfma_f32_16x16x32_bf16 v[104:107], v[92:95], v[236:239], v[104:107]
	v_mfma_f32_16x16x32_bf16 v[76:79], v[84:87], v[244:247], v[76:79]
	v_mfma_f32_16x16x32_bf16 v[72:75], v[92:95], v[244:247], v[72:75]
	s_setprio 0
	s_setprio 1
	v_mfma_f32_16x16x32_bf16 v[136:139], v[144:147], v[208:211], v[136:139]
	v_mfma_f32_16x16x32_bf16 v[128:131], v[152:155], v[208:211], v[128:131]
	v_mfma_f32_16x16x32_bf16 v[116:119], v[144:147], v[216:219], v[116:119]
	v_mfma_f32_16x16x32_bf16 v[112:115], v[152:155], v[216:219], v[112:115]
	v_mfma_f32_16x16x32_bf16 v[100:103], v[144:147], v[232:235], v[100:103]
	v_mfma_f32_16x16x32_bf16 v[96:99], v[152:155], v[232:235], v[96:99]
	v_mfma_f32_16x16x32_bf16 v[68:71], v[144:147], v[240:243], v[68:71]
	v_mfma_f32_16x16x32_bf16 v[64:67], v[152:155], v[240:243], v[64:67]
	v_mfma_f32_16x16x32_bf16 v[136:139], v[148:151], v[212:215], v[136:139]
	v_mfma_f32_16x16x32_bf16 v[128:131], v[156:159], v[212:215], v[128:131]
	v_mfma_f32_16x16x32_bf16 v[116:119], v[148:151], v[220:223], v[116:119]
	v_mfma_f32_16x16x32_bf16 v[112:115], v[156:159], v[220:223], v[112:115]
	v_mfma_f32_16x16x32_bf16 v[100:103], v[148:151], v[236:239], v[100:103]
	v_mfma_f32_16x16x32_bf16 v[96:99], v[156:159], v[236:239], v[96:99]
	v_mfma_f32_16x16x32_bf16 v[68:71], v[148:151], v[244:247], v[68:71]
	v_mfma_f32_16x16x32_bf16 v[64:67], v[156:159], v[244:247], v[64:67]
	s_barrier
	s_setprio 0
	s_add_i32 s16, s49, s18
	v_lshl_add_u64 v[192:193], v[192:193], 0, s[76:77]
	s_mov_b32 m0, s16
	ds_read_b128 v[208:211], v203 offset:49152
	ds_read_b128 v[212:215], v203 offset:50176
	ds_read_b128 v[216:219], v203 offset:51200
	ds_read_b128 v[220:223], v203 offset:52224
	ds_read_b128 v[232:235], v203 offset:53248
	ds_read_b128 v[236:239], v203 offset:54272
	ds_read_b128 v[240:243], v203 offset:55296
	ds_read_b128 v[244:247], v203 offset:56320
	global_load_lds_dwordx4 v[192:193], off
	s_add_i32 m0, s16, 0x2000
	s_add_u32 s14, s14, 0x80080
	v_lshl_add_u64 v[192:193], v[248:249], 0, s[76:77]
	s_addc_u32 s15, s15, 0
	s_add_i32 s16, s50, s18
	global_load_lds_dwordx4 v[192:193], off
	v_lshl_add_u64 v[192:193], s[14:15], 0, v[166:167]
	s_mov_b32 m0, s16
	s_nop 0
	global_load_lds_dwordx4 v[192:193], off
	v_lshl_add_u64 v[192:193], s[14:15], 0, v[170:171]
	s_add_i32 m0, s16, 0x2000
	s_nop 0
	global_load_lds_dwordx4 v[192:193], off
	v_lshl_add_u64 v[192:193], v[250:251], 0, s[76:77]
	s_mov_b32 m0, s27
	s_nop 0
	global_load_lds_dwordx4 v[192:193], off
	v_lshl_add_u64 v[192:193], v[252:253], 0, s[76:77]
	s_mov_b32 m0, s28
	s_nop 0
	global_load_lds_dwordx4 v[192:193], off
	s_waitcnt vmcnt(8)
	s_waitcnt lgkmcnt(0)
	s_setprio 1
	s_barrier
	v_mfma_f32_16x16x32_bf16 v[60:63], v[80:83], v[208:211], v[60:63]
	v_mfma_f32_16x16x32_bf16 v[56:59], v[88:91], v[208:211], v[56:59]
	v_mfma_f32_16x16x32_bf16 v[44:47], v[80:83], v[216:219], v[44:47]
	v_mfma_f32_16x16x32_bf16 v[40:43], v[88:91], v[216:219], v[40:43]
	v_mfma_f32_16x16x32_bf16 v[28:31], v[80:83], v[232:235], v[28:31]
	v_mfma_f32_16x16x32_bf16 v[24:27], v[88:91], v[232:235], v[24:27]
	v_mfma_f32_16x16x32_bf16 v[12:15], v[80:83], v[240:243], v[12:15]
	v_mfma_f32_16x16x32_bf16 v[8:11], v[88:91], v[240:243], v[8:11]
	v_mfma_f32_16x16x32_bf16 v[60:63], v[84:87], v[212:215], v[60:63]
	v_mfma_f32_16x16x32_bf16 v[56:59], v[92:95], v[212:215], v[56:59]
	v_mfma_f32_16x16x32_bf16 v[44:47], v[84:87], v[220:223], v[44:47]
	v_mfma_f32_16x16x32_bf16 v[40:43], v[92:95], v[220:223], v[40:43]
	v_mfma_f32_16x16x32_bf16 v[28:31], v[84:87], v[236:239], v[28:31]
	v_mfma_f32_16x16x32_bf16 v[24:27], v[92:95], v[236:239], v[24:27]
	v_mfma_f32_16x16x32_bf16 v[12:15], v[84:87], v[244:247], v[12:15]
	v_mfma_f32_16x16x32_bf16 v[8:11], v[92:95], v[244:247], v[8:11]
	s_setprio 0
	s_setprio 1
	v_mfma_f32_16x16x32_bf16 v[52:55], v[144:147], v[208:211], v[52:55]
	v_mfma_f32_16x16x32_bf16 v[48:51], v[152:155], v[208:211], v[48:51]
	v_mfma_f32_16x16x32_bf16 v[36:39], v[144:147], v[216:219], v[36:39]
	v_mfma_f32_16x16x32_bf16 v[32:35], v[152:155], v[216:219], v[32:35]
	v_mfma_f32_16x16x32_bf16 v[20:23], v[144:147], v[232:235], v[20:23]
	v_mfma_f32_16x16x32_bf16 v[16:19], v[152:155], v[232:235], v[16:19]
	v_mfma_f32_16x16x32_bf16 v[4:7], v[144:147], v[240:243], v[4:7]
	v_mfma_f32_16x16x32_bf16 v[0:3], v[152:155], v[240:243], v[0:3]
	v_mfma_f32_16x16x32_bf16 v[52:55], v[148:151], v[212:215], v[52:55]
	v_mfma_f32_16x16x32_bf16 v[48:51], v[156:159], v[212:215], v[48:51]
	v_mfma_f32_16x16x32_bf16 v[36:39], v[148:151], v[220:223], v[36:39]
	v_mfma_f32_16x16x32_bf16 v[32:35], v[156:159], v[220:223], v[32:35]
	v_mfma_f32_16x16x32_bf16 v[20:23], v[148:151], v[236:239], v[20:23]
	v_mfma_f32_16x16x32_bf16 v[16:19], v[156:159], v[236:239], v[16:19]
	v_mfma_f32_16x16x32_bf16 v[4:7], v[148:151], v[244:247], v[4:7]
	v_mfma_f32_16x16x32_bf16 v[0:3], v[156:159], v[244:247], v[0:3]
	s_barrier
	s_setprio 0
	s_add_i32 s48, s48, 2
	s_add_u32 s10, s10, 0x100
	s_addc_u32 s11, s11, 0
	s_add_u32 s46, s46, 0x100
	s_addc_u32 s47, s47, 0

; #define PG8_STAGE(bufoff, gbase, voff) do { _Pragma("unroll") for (int _i = 0; _i < 2; ++_i) \
;         __builtin_amdgcn_global_load_lds((const unsigned*)((const char*)(gbase) + (voff)[_i]), (PG8_LAS unsigned*)(lds + (bufoff) + ldsw + _i * 8192), 16, 0, 0); } while (0)
; #define PG8_LDA(dst, b, h) do { _Pragma("unroll") for (int m = 0; m < 4; ++m) _Pragma("unroll") for (int k = 0; k < 2; ++k) dst[m][k] = *(const PG8_LAS bf16x8*)(lds + PG8_SA(b, h) + aoff + m * 2048 + k * 1024); } while (0)
; #define PG8_LDB(dst, b, h) do { _Pragma("unroll") for (int n = 0; n < 2; ++n) _Pragma("unroll") for (int k = 0; k < 2; ++k) dst[n][k] = *(const PG8_LAS bf16x8*)(lds + PG8_SB(b, h) + boff + n * 2048 + k * 1024); } while (0)
; #define PG8_MMA(ai, bj, At, Bt) do { __builtin_amdgcn_s_setprio(1); _Pragma("unroll") for (int m = 0; m < 4; ++m) _Pragma("unroll") for (int n = 0; n < 2; ++n) _Pragma("unroll") for (int k = 0; k < 2; ++k) \
;         acc[ai][bj][m][n] = __builtin_amdgcn_mfma_f32_16x16x32_bf16(Bt[n][k], At[m][k], acc[ai][bj][m][n], 0, 0, 0); __builtin_amdgcn_s_setprio(0); } while (0)
; #define PG8_WAIT_V(n) asm volatile("s_waitcnt vmcnt(" #n ")" ::: "memory")
; #define PG8_BAR __builtin_amdgcn_s_barrier()
; template <class Epi, class Sched, bool ALIGN_EPI = false, bool SP2 = false, bool DUAL = false>
; __device__ __forceinline__ void gemm_phase(PG8_LAS unsigned char* lds, const Gemm g, const Sched& S, const Epi& E) {
;     ...
;         for (int t = 0; t < nt; t += 2) {
;             const bool last = (t == nt - 2);
;             const char* a1 = cA + (size_t)(t + 1) * kstep;
;             const char* a2 = last ? nA : cA + (size_t)(t + 2) * kstep; const char* b2 = last ? nB : cB + (size_t)(t + 2) * kstep;
;             const char* a3 = a2 + kstep; const char* b3 = b2 + kstep;
;             if (last && has_next) S.a_ready(nxt);
;             if constexpr (SP2) {
;             PG8_LDB(B0, 0, 0); PG8_LDB(B1, 0, 1); PG8_SCHED; PG8_LDA(At, 0, 0); PG8_STAGE(PG8_SA(1, 1), a1 + hstep, voffA);
;             PG8_WAIT_V(8); PG8_WAIT_L(0); PG8_BAR; PG8_MMA(0, 0, At, B0); PG8_MMA(0, 1, At, B1); PG8_BAR; PG8_SCHED;
;             PG8_LDA(At, 0, 1); PG8_STAGE(PG8_SB(0, 0), b2, voffB); PG8_STAGE(PG8_SB(0, 1), b2 + hstep, voffB); PG8_STAGE(PG8_SA(0, 0), a2, voffA);
;             PG8_WAIT_V(8); PG8_WAIT_L(0); PG8_BAR; PG8_MMA(1, 0, At, B0); PG8_MMA(1, 1, At, B1); PG8_BAR; PG8_SCHED;
.LBB0_895:
	s_ashr_i32 s61, s60, 31
	s_lshl_b64 s[18:19], s[60:61], 20
	s_add_u32 s62, s10, s18
	s_addc_u32 s63, s11, s19
	s_and_b64 s[18:19], s[6:7], exec
	s_cselect_b32 s18, s63, s17
	s_cselect_b32 s19, s62, s16
	s_ashr_i32 s41, s40, 31
	s_lshl_b64 s[64:65], s[40:41], 20
	s_add_u32 s64, s12, s64
	s_addc_u32 s65, s13, s65
	s_and_b64 s[68:69], s[6:7], exec
	s_cselect_b32 s41, s65, s15
	s_cselect_b32 s61, s64, s14
	s_add_u32 s68, s16, 0x80080
	s_addc_u32 s69, s17, 0
	s_add_u32 s67, s14, 0x100
	s_addc_u32 s70, s15, 0
	s_mov_b32 s71, -2
	s_waitcnt lgkmcnt(0)
	s_add_u32 s14, s68, 0xfff80080
	s_addc_u32 s15, s69, -1
	s_cmp_eq_u32 s71, 28
	s_cselect_b32 s17, s18, s15
	s_cselect_b32 s16, s19, s14
	s_cselect_b32 s15, s41, s70
	s_cselect_b32 s14, s61, s67
	s_waitcnt vmcnt(8)
	s_waitcnt lgkmcnt(0)
	s_setprio 1
	s_barrier
	v_mfma_f32_16x16x32_bf16 v[124:127], v[128:131], v[160:163], 0
	v_mfma_f32_16x16x32_bf16 v[120:123], v[136:139], v[160:163], 0
	v_mfma_f32_16x16x32_bf16 v[108:111], v[128:131], v[168:171], 0
	v_mfma_f32_16x16x32_bf16 v[104:107], v[136:139], v[168:171], 0
	v_mfma_f32_16x16x32_bf16 v[92:95], v[128:131], v[196:199], 0
	v_mfma_f32_16x16x32_bf16 v[88:91], v[136:139], v[196:199], 0
	v_mfma_f32_16x16x32_bf16 v[76:79], v[128:131], v[206:209], 0
	v_mfma_f32_16x16x32_bf16 v[72:75], v[136:139], v[206:209], 0
	v_mfma_f32_16x16x32_bf16 v[124:127], v[132:135], v[164:167], v[124:127]
	v_mfma_f32_16x16x32_bf16 v[120:123], v[140:143], v[164:167], v[120:123]
	v_mfma_f32_16x16x32_bf16 v[108:111], v[132:135], v[172:175], v[108:111]
	v_mfma_f32_16x16x32_bf16 v[104:107], v[140:143], v[172:175], v[104:107]
	v_mfma_f32_16x16x32_bf16 v[92:95], v[132:135], v[202:205], v[92:95]
	v_mfma_f32_16x16x32_bf16 v[88:91], v[140:143], v[202:205], v[88:91]
	v_mfma_f32_16x16x32_bf16 v[76:79], v[132:135], v[232:235], v[76:79]
	v_mfma_f32_16x16x32_bf16 v[72:75], v[140:143], v[232:235], v[72:75]
	s_setprio 0
	s_setprio 1
	v_mfma_f32_16x16x32_bf16 v[116:119], v[144:147], v[160:163], 0
	v_mfma_f32_16x16x32_bf16 v[112:115], v[152:155], v[160:163], 0
	v_mfma_f32_16x16x32_bf16 v[100:103], v[144:147], v[168:171], 0
	v_mfma_f32_16x16x32_bf16 v[96:99], v[152:155], v[168:171], 0
	v_mfma_f32_16x16x32_bf16 v[84:87], v[144:147], v[196:199], 0
	v_mfma_f32_16x16x32_bf16 v[80:83], v[152:155], v[196:199], 0
	v_mfma_f32_16x16x32_bf16 v[68:71], v[144:147], v[206:209], 0
	v_mfma_f32_16x16x32_bf16 v[64:67], v[152:155], v[206:209], 0
	v_mfma_f32_16x16x32_bf16 v[116:119], v[148:151], v[164:167], v[116:119]
	v_mfma_f32_16x16x32_bf16 v[112:115], v[156:159], v[164:167], v[112:115]
	v_mfma_f32_16x16x32_bf16 v[100:103], v[148:151], v[172:175], v[100:103]
	v_mfma_f32_16x16x32_bf16 v[96:99], v[156:159], v[172:175], v[96:99]
	v_mfma_f32_16x16x32_bf16 v[84:87], v[148:151], v[202:205], v[84:87]
	v_mfma_f32_16x16x32_bf16 v[80:83], v[156:159], v[202:205], v[80:83]
	v_mfma_f32_16x16x32_bf16 v[68:71], v[148:151], v[232:235], v[68:71]
	v_mfma_f32_16x16x32_bf16 v[64:67], v[156:159], v[232:235], v[64:67]
	s_barrier
	s_setprio 0
	v_lshl_add_u64 v[222:223], s[68:69], 0, v[188:189]
	s_add_i32 m0, s27, 0xc000
	s_nop 0
	global_load_lds_dwordx4 v[222:223], off
	v_lshl_add_u64 v[222:223], s[68:69], 0, v[190:191]
	s_add_i32 m0, s27, 0xe000
	s_nop 0
	global_load_lds_dwordx4 v[222:223], off
	s_add_i32 s72, s48, s26
	v_lshl_add_u64 v[222:223], s[14:15], 0, v[182:183]
	s_mov_b32 m0, s72
	ds_read_b128 v[160:163], v220 offset:16384
	ds_read_b128 v[164:167], v220 offset:17408
	ds_read_b128 v[168:171], v220 offset:18432
	ds_read_b128 v[172:175], v220 offset:19456
	ds_read_b128 v[196:199], v220 offset:20480
	ds_read_b128 v[202:205], v220 offset:21504
	ds_read_b128 v[206:209], v220 offset:22528
	ds_read_b128 v[232:235], v220 offset:23552
	global_load_lds_dwordx4 v[222:223], off
	s_add_i32 m0, s72, 0x2000
	s_add_u32 s72, s14, 0x80000
	v_lshl_add_u64 v[228:229], s[14:15], 0, v[186:187]
	s_addc_u32 s73, s15, 0
	s_add_i32 s74, s49, s26
	global_load_lds_dwordx4 v[228:229], off
	v_lshl_add_u64 v[236:237], s[72:73], 0, v[182:183]
	s_mov_b32 m0, s74
	v_lshl_add_u64 v[238:239], s[16:17], 0, v[184:185]
	global_load_lds_dwordx4 v[236:237], off
	v_lshl_add_u64 v[236:237], s[72:73], 0, v[186:187]
	s_add_i32 m0, s74, 0x2000
	s_nop 0
	global_load_lds_dwordx4 v[236:237], off
	v_lshl_add_u64 v[236:237], s[16:17], 0, v[180:181]
	s_mov_b32 m0, s27
	s_nop 0
	global_load_lds_dwordx4 v[236:237], off
	s_mov_b32 m0, s28
	s_nop 0
	global_load_lds_dwordx4 v[238:239], off
	s_waitcnt vmcnt(8)
	s_waitcnt lgkmcnt(0)
	s_setprio 1
	s_barrier
	v_mfma_f32_16x16x32_bf16 v[60:63], v[128:131], v[160:163], 0
	v_mfma_f32_16x16x32_bf16 v[56:59], v[136:139], v[160:163], 0
	v_mfma_f32_16x16x32_bf16 v[44:47], v[128:131], v[168:171], 0
	v_mfma_f32_16x16x32_bf16 v[40:43], v[136:139], v[168:171], 0
	v_mfma_f32_16x16x32_bf16 v[28:31], v[128:131], v[196:199], 0
	v_mfma_f32_16x16x32_bf16 v[24:27], v[136:139], v[196:199], 0
	v_mfma_f32_16x16x32_bf16 v[12:15], v[128:131], v[206:209], 0
	v_mfma_f32_16x16x32_bf16 v[8:11], v[136:139], v[206:209], 0
	v_mfma_f32_16x16x32_bf16 v[60:63], v[132:135], v[164:167], v[60:63]
	v_mfma_f32_16x16x32_bf16 v[56:59], v[140:143], v[164:167], v[56:59]
	v_mfma_f32_16x16x32_bf16 v[44:47], v[132:135], v[172:175], v[44:47]
	v_mfma_f32_16x16x32_bf16 v[40:43], v[140:143], v[172:175], v[40:43]
	v_mfma_f32_16x16x32_bf16 v[28:31], v[132:135], v[202:205], v[28:31]
	v_mfma_f32_16x16x32_bf16 v[24:27], v[140:143], v[202:205], v[24:27]
	v_mfma_f32_16x16x32_bf16 v[12:15], v[132:135], v[232:235], v[12:15]
	v_mfma_f32_16x16x32_bf16 v[8:11], v[140:143], v[232:235], v[8:11]
	s_setprio 0
	s_setprio 1
	v_mfma_f32_16x16x32_bf16 v[52:55], v[144:147], v[160:163], 0
	v_mfma_f32_16x16x32_bf16 v[48:51], v[152:155], v[160:163], 0
	v_mfma_f32_16x16x32_bf16 v[36:39], v[144:147], v[168:171], 0
	v_mfma_f32_16x16x32_bf16 v[32:35], v[152:155], v[168:171], 0
	v_mfma_f32_16x16x32_bf16 v[20:23], v[144:147], v[196:199], 0
	v_mfma_f32_16x16x32_bf16 v[16:19], v[152:155], v[196:199], 0
	v_mfma_f32_16x16x32_bf16 v[4:7], v[144:147], v[206:209], 0
	v_mfma_f32_16x16x32_bf16 v[0:3], v[152:155], v[206:209], 0
	v_mfma_f32_16x16x32_bf16 v[52:55], v[148:151], v[164:167], v[52:55]
	v_mfma_f32_16x16x32_bf16 v[48:51], v[156:159], v[164:167], v[48:51]
	v_mfma_f32_16x16x32_bf16 v[36:39], v[148:151], v[172:175], v[36:39]
	v_mfma_f32_16x16x32_bf16 v[32:35], v[156:159], v[172:175], v[32:35]
	v_mfma_f32_16x16x32_bf16 v[20:23], v[148:151], v[202:205], v[20:23]
	v_mfma_f32_16x16x32_bf16 v[16:19], v[156:159], v[202:205], v[16:19]
	v_mfma_f32_16x16x32_bf16 v[4:7], v[148:151], v[232:235], v[4:7]
	v_mfma_f32_16x16x32_bf16 v[0:3], v[156:159], v[232:235], v[0:3]
	s_barrier
; #define PG8_STAGE(bufoff, gbase, voff) do { _Pragma("unroll") for (int _i = 0; _i < 2; ++_i) \
;         __builtin_amdgcn_global_load_lds((const unsigned*)((const char*)(gbase) + (voff)[_i]), (PG8_LAS unsigned*)(lds + (bufoff) + ldsw + _i * 8192), 16, 0, 0); } while (0)
; #define PG8_LDA(dst, b, h) do { _Pragma("unroll") for (int m = 0; m < 4; ++m) _Pragma("unroll") for (int k = 0; k < 2; ++k) dst[m][k] = *(const PG8_LAS bf16x8*)(lds + PG8_SA(b, h) + aoff + m * 2048 + k * 1024); } while (0)
; #define PG8_LDB(dst, b, h) do { _Pragma("unroll") for (int n = 0; n < 2; ++n) _Pragma("unroll") for (int k = 0; k < 2; ++k) dst[n][k] = *(const PG8_LAS bf16x8*)(lds + PG8_SB(b, h) + boff + n * 2048 + k * 1024); } while (0)
; #define PG8_MMA(ai, bj, At, Bt) do { __builtin_amdgcn_s_setprio(1); _Pragma("unroll") for (int m = 0; m < 4; ++m) _Pragma("unroll") for (int n = 0; n < 2; ++n) _Pragma("unroll") for (int k = 0; k < 2; ++k) \
;         acc[ai][bj][m][n] = __builtin_amdgcn_mfma_f32_16x16x32_bf16(Bt[n][k], At[m][k], acc[ai][bj][m][n], 0, 0, 0); __builtin_amdgcn_s_setprio(0); } while (0)
; #define PG8_WAIT_V(n) asm volatile("s_waitcnt vmcnt(" #n ")" ::: "memory")
; #define PG8_WAIT_L(n) asm volatile("s_waitcnt lgkmcnt(" #n ")" ::: "memory")
; #define PG8_BAR __builtin_amdgcn_s_barrier()
; #define PG8_SCHED __builtin_amdgcn_sched_barrier(0)
; template <class Epi, class Sched, bool ALIGN_EPI = false, bool SP2 = false, bool DUAL = false>
; __device__ __forceinline__ void gemm_phase(PG8_LAS unsigned char* lds, const Gemm g, const Sched& S, const Epi& E) {
;     ...
;             PG8_LDB(B0, 1, 0); PG8_LDB(B1, 1, 1); PG8_SCHED; PG8_LDA(At, 1, 0); PG8_STAGE(PG8_SA(0, 1), a2 + hstep, voffA);
;             PG8_WAIT_V(8); PG8_WAIT_L(0); PG8_BAR; PG8_MMA(0, 0, At, B0); PG8_MMA(0, 1, At, B1); PG8_BAR; PG8_SCHED;
	s_setprio 0
	s_add_i32 s72, 0, 0x18000
	s_add_i32 s73, 0, 0x1c000
	v_add_u32_e32 v140, s72, v216
	v_add_u32_e32 v156, s73, v216
	ds_read_b128 v[128:131], v140
	ds_read_b128 v[132:135], v140 offset:1024
	ds_read_b128 v[136:139], v140 offset:2048
	ds_read_b128 v[140:143], v140 offset:3072
	ds_read_b128 v[144:147], v156
	ds_read_b128 v[148:151], v156 offset:1024
	ds_read_b128 v[152:155], v156 offset:2048
	ds_read_b128 v[156:159], v156 offset:3072
	s_add_u32 s16, s16, 0x80000
	s_addc_u32 s17, s17, 0
	s_mov_b32 m0, s29
	v_lshl_add_u64 v[240:241], s[16:17], 0, v[180:181]
	ds_read_b128 v[160:163], v220 offset:32768
	ds_read_b128 v[164:167], v220 offset:33792
	ds_read_b128 v[168:171], v220 offset:34816
	ds_read_b128 v[172:175], v220 offset:35840
	ds_read_b128 v[196:199], v220 offset:36864
	ds_read_b128 v[202:205], v220 offset:37888
	ds_read_b128 v[206:209], v220 offset:38912
	ds_read_b128 v[232:235], v220 offset:39936
	global_load_lds_dwordx4 v[240:241], off
	v_lshl_add_u64 v[240:241], s[16:17], 0, v[184:185]
	s_mov_b32 m0, s34
	s_nop 0
	global_load_lds_dwordx4 v[240:241], off
	s_waitcnt vmcnt(8)
	s_waitcnt lgkmcnt(0)
	s_setprio 1
	s_barrier
	v_mfma_f32_16x16x32_bf16 v[124:127], v[128:131], v[160:163], v[124:127]
	v_mfma_f32_16x16x32_bf16 v[120:123], v[136:139], v[160:163], v[120:123]
	v_mfma_f32_16x16x32_bf16 v[108:111], v[128:131], v[168:171], v[108:111]
	v_mfma_f32_16x16x32_bf16 v[104:107], v[136:139], v[168:171], v[104:107]
	v_mfma_f32_16x16x32_bf16 v[92:95], v[128:131], v[196:199], v[92:95]
	v_mfma_f32_16x16x32_bf16 v[88:91], v[136:139], v[196:199], v[88:91]
	v_mfma_f32_16x16x32_bf16 v[76:79], v[128:131], v[206:209], v[76:79]
	v_mfma_f32_16x16x32_bf16 v[72:75], v[136:139], v[206:209], v[72:75]
	v_mfma_f32_16x16x32_bf16 v[124:127], v[132:135], v[164:167], v[124:127]
	v_mfma_f32_16x16x32_bf16 v[120:123], v[140:143], v[164:167], v[120:123]
	v_mfma_f32_16x16x32_bf16 v[108:111], v[132:135], v[172:175], v[108:111]
	v_mfma_f32_16x16x32_bf16 v[104:107], v[140:143], v[172:175], v[104:107]
	v_mfma_f32_16x16x32_bf16 v[92:95], v[132:135], v[202:205], v[92:95]
	v_mfma_f32_16x16x32_bf16 v[88:91], v[140:143], v[202:205], v[88:91]
	v_mfma_f32_16x16x32_bf16 v[76:79], v[132:135], v[232:235], v[76:79]
	v_mfma_f32_16x16x32_bf16 v[72:75], v[140:143], v[232:235], v[72:75]
	s_setprio 0
	s_setprio 1
	v_mfma_f32_16x16x32_bf16 v[116:119], v[144:147], v[160:163], v[116:119]
	v_mfma_f32_16x16x32_bf16 v[112:115], v[152:155], v[160:163], v[112:115]
	v_mfma_f32_16x16x32_bf16 v[100:103], v[144:147], v[168:171], v[100:103]
	v_mfma_f32_16x16x32_bf16 v[96:99], v[152:155], v[168:171], v[96:99]
	v_mfma_f32_16x16x32_bf16 v[84:87], v[144:147], v[196:199], v[84:87]
	v_mfma_f32_16x16x32_bf16 v[80:83], v[152:155], v[196:199], v[80:83]
	v_mfma_f32_16x16x32_bf16 v[68:71], v[144:147], v[206:209], v[68:71]
	v_mfma_f32_16x16x32_bf16 v[64:67], v[152:155], v[206:209], v[64:67]
	v_mfma_f32_16x16x32_bf16 v[116:119], v[148:151], v[164:167], v[116:119]
	v_mfma_f32_16x16x32_bf16 v[112:115], v[156:159], v[164:167], v[112:115]
	v_mfma_f32_16x16x32_bf16 v[100:103], v[148:151], v[172:175], v[100:103]
	v_mfma_f32_16x16x32_bf16 v[96:99], v[156:159], v[172:175], v[96:99]
	v_mfma_f32_16x16x32_bf16 v[84:87], v[148:151], v[202:205], v[84:87]
	v_mfma_f32_16x16x32_bf16 v[80:83], v[156:159], v[202:205], v[80:83]
	v_mfma_f32_16x16x32_bf16 v[68:71], v[148:151], v[232:235], v[68:71]
	v_mfma_f32_16x16x32_bf16 v[64:67], v[156:159], v[232:235], v[64:67]
	s_barrier
; #define PG8_STAGE(bufoff, gbase, voff) do { _Pragma("unroll") for (int _i = 0; _i < 2; ++_i) \
;         __builtin_amdgcn_global_load_lds((const unsigned*)((const char*)(gbase) + (voff)[_i]), (PG8_LAS unsigned*)(lds + (bufoff) + ldsw + _i * 8192), 16, 0, 0); } while (0)
; #define PG8_LDA(dst, b, h) do { _Pragma("unroll") for (int m = 0; m < 4; ++m) _Pragma("unroll") for (int k = 0; k < 2; ++k) dst[m][k] = *(const PG8_LAS bf16x8*)(lds + PG8_SA(b, h) + aoff + m * 2048 + k * 1024); } while (0)
; #define PG8_MMA(ai, bj, At, Bt) do { __builtin_amdgcn_s_setprio(1); _Pragma("unroll") for (int m = 0; m < 4; ++m) _Pragma("unroll") for (int n = 0; n < 2; ++n) _Pragma("unroll") for (int k = 0; k < 2; ++k) \
;         acc[ai][bj][m][n] = __builtin_amdgcn_mfma_f32_16x16x32_bf16(Bt[n][k], At[m][k], acc[ai][bj][m][n], 0, 0, 0); __builtin_amdgcn_s_setprio(0); } while (0)
; #define PG8_WAIT_V(n) asm volatile("s_waitcnt vmcnt(" #n ")" ::: "memory")
; #define PG8_WAIT_L(n) asm volatile("s_waitcnt lgkmcnt(" #n ")" ::: "memory")
; #define PG8_BAR __builtin_amdgcn_s_barrier()
; #define PG8_SCHED __builtin_amdgcn_sched_barrier(0)
; template <class Epi, class Sched, bool ALIGN_EPI = false, bool SP2 = false, bool DUAL = false>
; __device__ __forceinline__ void gemm_phase(PG8_LAS unsigned char* lds, const Gemm g, const Sched& S, const Epi& E) {
;     ...
;             PG8_LDA(At, 1, 1); PG8_STAGE(PG8_SB(1, 0), b3, voffB); PG8_STAGE(PG8_SB(1, 1), b3 + hstep, voffB); PG8_STAGE(PG8_SA(1, 0), a3, voffA);
;             PG8_WAIT_V(8); PG8_WAIT_L(0); PG8_BAR; PG8_MMA(1, 0, At, B0); PG8_MMA(1, 1, At, B1); PG8_BAR; PG8_SCHED;
	s_setprio 0
	s_add_i32 s16, s72, s26
	v_lshl_add_u64 v[222:223], v[222:223], 0, s[36:37]
	s_mov_b32 m0, s16
	ds_read_b128 v[160:163], v220 offset:49152
	ds_read_b128 v[164:167], v220 offset:50176
	ds_read_b128 v[168:171], v220 offset:51200
	ds_read_b128 v[172:175], v220 offset:52224
	ds_read_b128 v[196:199], v220 offset:53248
	ds_read_b128 v[202:205], v220 offset:54272
	ds_read_b128 v[206:209], v220 offset:55296
	ds_read_b128 v[232:235], v220 offset:56320
	global_load_lds_dwordx4 v[222:223], off
	s_add_i32 m0, s16, 0x2000
	s_add_u32 s14, s14, 0x80080
	v_lshl_add_u64 v[222:223], v[228:229], 0, s[36:37]
	s_addc_u32 s15, s15, 0
	s_add_i32 s16, s73, s26
	global_load_lds_dwordx4 v[222:223], off
	v_lshl_add_u64 v[222:223], s[14:15], 0, v[182:183]
	s_mov_b32 m0, s16
	s_nop 0
	global_load_lds_dwordx4 v[222:223], off
	v_lshl_add_u64 v[222:223], s[14:15], 0, v[186:187]
	s_add_i32 m0, s16, 0x2000
	s_nop 0
	global_load_lds_dwordx4 v[222:223], off
	v_lshl_add_u64 v[222:223], v[236:237], 0, s[36:37]
	s_mov_b32 m0, s44
	s_nop 0
	global_load_lds_dwordx4 v[222:223], off
	v_lshl_add_u64 v[222:223], v[238:239], 0, s[36:37]
	s_mov_b32 m0, s45
	s_nop 0
	global_load_lds_dwordx4 v[222:223], off
	s_waitcnt vmcnt(8)
	s_waitcnt lgkmcnt(0)
	s_setprio 1
	s_barrier
	v_mfma_f32_16x16x32_bf16 v[60:63], v[128:131], v[160:163], v[60:63]
	v_mfma_f32_16x16x32_bf16 v[56:59], v[136:139], v[160:163], v[56:59]
	v_mfma_f32_16x16x32_bf16 v[44:47], v[128:131], v[168:171], v[44:47]
	v_mfma_f32_16x16x32_bf16 v[40:43], v[136:139], v[168:171], v[40:43]
	v_mfma_f32_16x16x32_bf16 v[28:31], v[128:131], v[196:199], v[28:31]
	v_mfma_f32_16x16x32_bf16 v[24:27], v[136:139], v[196:199], v[24:27]
	v_mfma_f32_16x16x32_bf16 v[12:15], v[128:131], v[206:209], v[12:15]
	v_mfma_f32_16x16x32_bf16 v[8:11], v[136:139], v[206:209], v[8:11]
	v_mfma_f32_16x16x32_bf16 v[60:63], v[132:135], v[164:167], v[60:63]
	v_mfma_f32_16x16x32_bf16 v[56:59], v[140:143], v[164:167], v[56:59]
	v_mfma_f32_16x16x32_bf16 v[44:47], v[132:135], v[172:175], v[44:47]
	v_mfma_f32_16x16x32_bf16 v[40:43], v[140:143], v[172:175], v[40:43]
	v_mfma_f32_16x16x32_bf16 v[28:31], v[132:135], v[202:205], v[28:31]
	v_mfma_f32_16x16x32_bf16 v[24:27], v[140:143], v[202:205], v[24:27]
	v_mfma_f32_16x16x32_bf16 v[12:15], v[132:135], v[232:235], v[12:15]
	v_mfma_f32_16x16x32_bf16 v[8:11], v[140:143], v[232:235], v[8:11]
	s_setprio 0
	s_setprio 1
	v_mfma_f32_16x16x32_bf16 v[52:55], v[144:147], v[160:163], v[52:55]
	v_mfma_f32_16x16x32_bf16 v[48:51], v[152:155], v[160:163], v[48:51]
	v_mfma_f32_16x16x32_bf16 v[36:39], v[144:147], v[168:171], v[36:39]
	v_mfma_f32_16x16x32_bf16 v[32:35], v[152:155], v[168:171], v[32:35]
	v_mfma_f32_16x16x32_bf16 v[20:23], v[144:147], v[196:199], v[20:23]
	v_mfma_f32_16x16x32_bf16 v[16:19], v[152:155], v[196:199], v[16:19]
	v_mfma_f32_16x16x32_bf16 v[4:7], v[144:147], v[206:209], v[4:7]
	v_mfma_f32_16x16x32_bf16 v[0:3], v[152:155], v[206:209], v[0:3]
	v_mfma_f32_16x16x32_bf16 v[52:55], v[148:151], v[164:167], v[52:55]
	v_mfma_f32_16x16x32_bf16 v[48:51], v[156:159], v[164:167], v[48:51]
	v_mfma_f32_16x16x32_bf16 v[36:39], v[148:151], v[172:175], v[36:39]
	v_mfma_f32_16x16x32_bf16 v[32:35], v[156:159], v[172:175], v[32:35]
	v_mfma_f32_16x16x32_bf16 v[20:23], v[148:151], v[202:205], v[20:23]
	v_mfma_f32_16x16x32_bf16 v[16:19], v[156:159], v[202:205], v[16:19]
	v_mfma_f32_16x16x32_bf16 v[4:7], v[148:151], v[232:235], v[4:7]
	v_mfma_f32_16x16x32_bf16 v[0:3], v[156:159], v[232:235], v[0:3]
	s_barrier
	s_setprio 0
	s_add_i32 s71, s71, 2
	s_add_u32 s68, s68, 0x100
	s_addc_u32 s69, s69, 0
	s_add_u32 s67, s67, 0x100
	s_addc_u32 s70, s70, 0

; #define PG8_STAGE(bufoff, gbase, voff) do { _Pragma("unroll") for (int _i = 0; _i < 2; ++_i) \
;         __builtin_amdgcn_global_load_lds((const unsigned*)((const char*)(gbase) + (voff)[_i]), (PG8_LAS unsigned*)(lds + (bufoff) + ldsw + _i * 8192), 16, 0, 0); } while (0)
; #define PG8_LDA(dst, b, h) do { _Pragma("unroll") for (int m = 0; m < 4; ++m) _Pragma("unroll") for (int k = 0; k < 2; ++k) dst[m][k] = *(const PG8_LAS bf16x8*)(lds + PG8_SA(b, h) + aoff + m * 2048 + k * 1024); } while (0)
; #define PG8_LDB(dst, b, h) do { _Pragma("unroll") for (int n = 0; n < 2; ++n) _Pragma("unroll") for (int k = 0; k < 2; ++k) dst[n][k] = *(const PG8_LAS bf16x8*)(lds + PG8_SB(b, h) + boff + n * 2048 + k * 1024); } while (0)
; #define PG8_MMA(ai, bj, At, Bt) do { __builtin_amdgcn_s_setprio(1); _Pragma("unroll") for (int m = 0; m < 4; ++m) _Pragma("unroll") for (int n = 0; n < 2; ++n) _Pragma("unroll") for (int k = 0; k < 2; ++k) \
;         acc[ai][bj][m][n] = __builtin_amdgcn_mfma_f32_16x16x32_bf16(Bt[n][k], At[m][k], acc[ai][bj][m][n], 0, 0, 0); __builtin_amdgcn_s_setprio(0); } while (0)
; #define PG8_WAIT_V(n) asm volatile("s_waitcnt vmcnt(" #n ")" ::: "memory")
; #define PG8_BAR __builtin_amdgcn_s_barrier()
; template <class Epi, class Sched, bool ALIGN_EPI = false, bool SP2 = false, bool DUAL = false>
; __device__ __forceinline__ void gemm_phase(PG8_LAS unsigned char* lds, const Gemm g, const Sched& S, const Epi& E) {
;     ...
;         for (int t = 0; t < nt; t += 2) {
;             const bool last = (t == nt - 2);
;             const char* a1 = cA + (size_t)(t + 1) * kstep;
;             const char* a2 = last ? nA : cA + (size_t)(t + 2) * kstep; const char* b2 = last ? nB : cB + (size_t)(t + 2) * kstep;
;             const char* a3 = a2 + kstep; const char* b3 = b2 + kstep;
;             if (last && has_next) S.a_ready(nxt);
;             if constexpr (SP2) {
;             PG8_LDB(B0, 0, 0); PG8_LDB(B1, 0, 1); PG8_SCHED; PG8_LDA(At, 0, 0); PG8_STAGE(PG8_SA(1, 1), a1 + hstep, voffA);
;             PG8_WAIT_V(8); PG8_WAIT_L(0); PG8_BAR; PG8_MMA(0, 0, At, B0); PG8_MMA(0, 1, At, B1); PG8_BAR; PG8_SCHED;
;             PG8_LDA(At, 0, 1); PG8_STAGE(PG8_SB(0, 0), b2, voffB); PG8_STAGE(PG8_SB(0, 1), b2 + hstep, voffB); PG8_STAGE(PG8_SA(0, 0), a2, voffA);
;             PG8_WAIT_V(8); PG8_WAIT_L(0); PG8_BAR; PG8_MMA(1, 0, At, B0); PG8_MMA(1, 1, At, B1); PG8_BAR; PG8_SCHED;
.LBB0_991:
	s_ashr_i32 s25, s24, 31
	s_lshl_b64 s[28:29], s[24:25], 20
	s_add_u32 s30, s19, s28
	s_addc_u32 s31, s21, s29
	s_and_b64 s[28:29], s[4:5], exec
	s_cselect_b32 s25, s31, s27
	s_cselect_b32 s28, s30, s26
	s_ashr_i32 s23, s22, 31
	s_lshl_b64 s[36:37], s[22:23], 20
	s_add_u32 s36, s8, s36
	s_addc_u32 s37, s9, s37
	s_and_b64 s[40:41], s[4:5], exec
	s_cselect_b32 s23, s37, s15
	s_cselect_b32 s29, s36, s14
	s_add_u32 s40, s26, 0x80080
	s_addc_u32 s41, s27, 0
	s_add_u32 s63, s14, 0x100
	s_addc_u32 s64, s15, 0
	s_mov_b32 s65, -2
	s_add_u32 s14, s40, 0xfff80080
	s_addc_u32 s15, s41, -1
	s_cmp_eq_u32 s65, 28
	s_cselect_b32 s27, s25, s15
	s_cselect_b32 s26, s28, s14
	s_cselect_b32 s15, s23, s64
	s_cselect_b32 s14, s29, s63
	s_waitcnt vmcnt(8)
	s_waitcnt lgkmcnt(0)
	s_setprio 1
	s_barrier
	v_mfma_f32_16x16x32_bf16 v[124:127], v[128:131], v[160:163], 0
	v_mfma_f32_16x16x32_bf16 v[120:123], v[136:139], v[160:163], 0
	v_mfma_f32_16x16x32_bf16 v[108:111], v[128:131], v[188:191], 0
	v_mfma_f32_16x16x32_bf16 v[104:107], v[136:139], v[188:191], 0
	v_mfma_f32_16x16x32_bf16 v[92:95], v[128:131], v[196:199], 0
	v_mfma_f32_16x16x32_bf16 v[88:91], v[136:139], v[196:199], 0
	v_mfma_f32_16x16x32_bf16 v[76:79], v[128:131], v[206:209], 0
	v_mfma_f32_16x16x32_bf16 v[72:75], v[136:139], v[206:209], 0
	v_mfma_f32_16x16x32_bf16 v[124:127], v[132:135], v[164:167], v[124:127]
	v_mfma_f32_16x16x32_bf16 v[120:123], v[140:143], v[164:167], v[120:123]
	v_mfma_f32_16x16x32_bf16 v[108:111], v[132:135], v[192:195], v[108:111]
	v_mfma_f32_16x16x32_bf16 v[104:107], v[140:143], v[192:195], v[104:107]
	v_mfma_f32_16x16x32_bf16 v[92:95], v[132:135], v[202:205], v[92:95]
	v_mfma_f32_16x16x32_bf16 v[88:91], v[140:143], v[202:205], v[88:91]
	v_mfma_f32_16x16x32_bf16 v[76:79], v[132:135], v[220:223], v[76:79]
	v_mfma_f32_16x16x32_bf16 v[72:75], v[140:143], v[220:223], v[72:75]
	s_setprio 0
	s_setprio 1
	v_mfma_f32_16x16x32_bf16 v[116:119], v[144:147], v[160:163], 0
	v_mfma_f32_16x16x32_bf16 v[112:115], v[152:155], v[160:163], 0
	v_mfma_f32_16x16x32_bf16 v[100:103], v[144:147], v[188:191], 0
	v_mfma_f32_16x16x32_bf16 v[96:99], v[152:155], v[188:191], 0
	v_mfma_f32_16x16x32_bf16 v[84:87], v[144:147], v[196:199], 0
	v_mfma_f32_16x16x32_bf16 v[80:83], v[152:155], v[196:199], 0
	v_mfma_f32_16x16x32_bf16 v[68:71], v[144:147], v[206:209], 0
	v_mfma_f32_16x16x32_bf16 v[64:67], v[152:155], v[206:209], 0
	v_mfma_f32_16x16x32_bf16 v[116:119], v[148:151], v[164:167], v[116:119]
	v_mfma_f32_16x16x32_bf16 v[112:115], v[156:159], v[164:167], v[112:115]
	v_mfma_f32_16x16x32_bf16 v[100:103], v[148:151], v[192:195], v[100:103]
	v_mfma_f32_16x16x32_bf16 v[96:99], v[156:159], v[192:195], v[96:99]
	v_mfma_f32_16x16x32_bf16 v[84:87], v[148:151], v[202:205], v[84:87]
	v_mfma_f32_16x16x32_bf16 v[80:83], v[156:159], v[202:205], v[80:83]
	v_mfma_f32_16x16x32_bf16 v[68:71], v[148:151], v[220:223], v[68:71]
	v_mfma_f32_16x16x32_bf16 v[64:67], v[156:159], v[220:223], v[64:67]
	s_barrier
	s_setprio 0
	v_lshl_add_u64 v[228:229], s[40:41], 0, v[180:181]
	s_add_i32 m0, s39, 0xc000
	s_nop 0
	global_load_lds_dwordx4 v[228:229], off
	v_lshl_add_u64 v[228:229], s[40:41], 0, v[182:183]
	s_add_i32 m0, s39, 0xe000
	s_nop 0
	global_load_lds_dwordx4 v[228:229], off
	s_add_i32 s66, s50, s34
	v_lshl_add_u64 v[228:229], s[14:15], 0, v[170:171]
	s_mov_b32 m0, s66
	ds_read_b128 v[160:163], v217 offset:16384
	ds_read_b128 v[164:167], v217 offset:17408
	ds_read_b128 v[188:191], v217 offset:18432
	ds_read_b128 v[192:195], v217 offset:19456
	ds_read_b128 v[196:199], v217 offset:20480
	ds_read_b128 v[202:205], v217 offset:21504
	ds_read_b128 v[206:209], v217 offset:22528
	ds_read_b128 v[220:223], v217 offset:23552
	global_load_lds_dwordx4 v[228:229], off
	s_add_i32 m0, s66, 0x2000
	s_add_u32 s66, s14, 0x80000
	v_lshl_add_u64 v[232:233], s[14:15], 0, v[174:175]
	s_addc_u32 s67, s15, 0
	s_add_i32 s68, s51, s34
	global_load_lds_dwordx4 v[232:233], off
	v_lshl_add_u64 v[234:235], s[66:67], 0, v[170:171]
	s_mov_b32 m0, s68
	v_lshl_add_u64 v[236:237], s[26:27], 0, v[172:173]
	global_load_lds_dwordx4 v[234:235], off
	v_lshl_add_u64 v[234:235], s[66:67], 0, v[174:175]
	s_add_i32 m0, s68, 0x2000
	s_nop 0
	global_load_lds_dwordx4 v[234:235], off
	v_lshl_add_u64 v[234:235], s[26:27], 0, v[168:169]
	s_mov_b32 m0, s39
	s_nop 0
	global_load_lds_dwordx4 v[234:235], off
	s_mov_b32 m0, s42
	s_nop 0
	global_load_lds_dwordx4 v[236:237], off
	s_waitcnt vmcnt(8)
	s_waitcnt lgkmcnt(0)
	s_setprio 1
	s_barrier
	v_mfma_f32_16x16x32_bf16 v[60:63], v[128:131], v[160:163], 0
	v_mfma_f32_16x16x32_bf16 v[56:59], v[136:139], v[160:163], 0
	v_mfma_f32_16x16x32_bf16 v[44:47], v[128:131], v[188:191], 0
	v_mfma_f32_16x16x32_bf16 v[40:43], v[136:139], v[188:191], 0
	v_mfma_f32_16x16x32_bf16 v[28:31], v[128:131], v[196:199], 0
	v_mfma_f32_16x16x32_bf16 v[24:27], v[136:139], v[196:199], 0
	v_mfma_f32_16x16x32_bf16 v[12:15], v[128:131], v[206:209], 0
	v_mfma_f32_16x16x32_bf16 v[8:11], v[136:139], v[206:209], 0
	v_mfma_f32_16x16x32_bf16 v[60:63], v[132:135], v[164:167], v[60:63]
	v_mfma_f32_16x16x32_bf16 v[56:59], v[140:143], v[164:167], v[56:59]
	v_mfma_f32_16x16x32_bf16 v[44:47], v[132:135], v[192:195], v[44:47]
	v_mfma_f32_16x16x32_bf16 v[40:43], v[140:143], v[192:195], v[40:43]
	v_mfma_f32_16x16x32_bf16 v[28:31], v[132:135], v[202:205], v[28:31]
	v_mfma_f32_16x16x32_bf16 v[24:27], v[140:143], v[202:205], v[24:27]
	v_mfma_f32_16x16x32_bf16 v[12:15], v[132:135], v[220:223], v[12:15]
	v_mfma_f32_16x16x32_bf16 v[8:11], v[140:143], v[220:223], v[8:11]
	s_setprio 0
	s_setprio 1
	v_mfma_f32_16x16x32_bf16 v[52:55], v[144:147], v[160:163], 0
	v_mfma_f32_16x16x32_bf16 v[48:51], v[152:155], v[160:163], 0
	v_mfma_f32_16x16x32_bf16 v[36:39], v[144:147], v[188:191], 0
	v_mfma_f32_16x16x32_bf16 v[32:35], v[152:155], v[188:191], 0
	v_mfma_f32_16x16x32_bf16 v[20:23], v[144:147], v[196:199], 0
	v_mfma_f32_16x16x32_bf16 v[16:19], v[152:155], v[196:199], 0
	v_mfma_f32_16x16x32_bf16 v[4:7], v[144:147], v[206:209], 0
	v_mfma_f32_16x16x32_bf16 v[0:3], v[152:155], v[206:209], 0
	v_mfma_f32_16x16x32_bf16 v[52:55], v[148:151], v[164:167], v[52:55]
	v_mfma_f32_16x16x32_bf16 v[48:51], v[156:159], v[164:167], v[48:51]
	v_mfma_f32_16x16x32_bf16 v[36:39], v[148:151], v[192:195], v[36:39]
	v_mfma_f32_16x16x32_bf16 v[32:35], v[156:159], v[192:195], v[32:35]
	v_mfma_f32_16x16x32_bf16 v[20:23], v[148:151], v[202:205], v[20:23]
	v_mfma_f32_16x16x32_bf16 v[16:19], v[156:159], v[202:205], v[16:19]
	v_mfma_f32_16x16x32_bf16 v[4:7], v[148:151], v[220:223], v[4:7]
	v_mfma_f32_16x16x32_bf16 v[0:3], v[156:159], v[220:223], v[0:3]
	s_barrier
; #define PG8_STAGE(bufoff, gbase, voff) do { _Pragma("unroll") for (int _i = 0; _i < 2; ++_i) \
;         __builtin_amdgcn_global_load_lds((const unsigned*)((const char*)(gbase) + (voff)[_i]), (PG8_LAS unsigned*)(lds + (bufoff) + ldsw + _i * 8192), 16, 0, 0); } while (0)
; #define PG8_LDA(dst, b, h) do { _Pragma("unroll") for (int m = 0; m < 4; ++m) _Pragma("unroll") for (int k = 0; k < 2; ++k) dst[m][k] = *(const PG8_LAS bf16x8*)(lds + PG8_SA(b, h) + aoff + m * 2048 + k * 1024); } while (0)
; #define PG8_LDB(dst, b, h) do { _Pragma("unroll") for (int n = 0; n < 2; ++n) _Pragma("unroll") for (int k = 0; k < 2; ++k) dst[n][k] = *(const PG8_LAS bf16x8*)(lds + PG8_SB(b, h) + boff + n * 2048 + k * 1024); } while (0)
; #define PG8_MMA(ai, bj, At, Bt) do { __builtin_amdgcn_s_setprio(1); _Pragma("unroll") for (int m = 0; m < 4; ++m) _Pragma("unroll") for (int n = 0; n < 2; ++n) _Pragma("unroll") for (int k = 0; k < 2; ++k) \
;         acc[ai][bj][m][n] = __builtin_amdgcn_mfma_f32_16x16x32_bf16(Bt[n][k], At[m][k], acc[ai][bj][m][n], 0, 0, 0); __builtin_amdgcn_s_setprio(0); } while (0)
; #define PG8_WAIT_V(n) asm volatile("s_waitcnt vmcnt(" #n ")" ::: "memory")
; #define PG8_WAIT_L(n) asm volatile("s_waitcnt lgkmcnt(" #n ")" ::: "memory")
; #define PG8_BAR __builtin_amdgcn_s_barrier()
; #define PG8_SCHED __builtin_amdgcn_sched_barrier(0)
; template <class Epi, class Sched, bool ALIGN_EPI = false, bool SP2 = false, bool DUAL = false>
; __device__ __forceinline__ void gemm_phase(PG8_LAS unsigned char* lds, const Gemm g, const Sched& S, const Epi& E) {
;     ...
;             PG8_LDB(B0, 1, 0); PG8_LDB(B1, 1, 1); PG8_SCHED; PG8_LDA(At, 1, 0); PG8_STAGE(PG8_SA(0, 1), a2 + hstep, voffA);
;             PG8_WAIT_V(8); PG8_WAIT_L(0); PG8_BAR; PG8_MMA(0, 0, At, B0); PG8_MMA(0, 1, At, B1); PG8_BAR; PG8_SCHED;
	s_setprio 0
	s_add_i32 s66, 0, 0x18000
	s_add_i32 s67, 0, 0x1c000
	v_add_u32_e32 v140, s66, v213
	v_add_u32_e32 v156, s67, v213
	ds_read_b128 v[128:131], v140
	ds_read_b128 v[132:135], v140 offset:1024
	ds_read_b128 v[136:139], v140 offset:2048
	ds_read_b128 v[140:143], v140 offset:3072
	ds_read_b128 v[144:147], v156
	ds_read_b128 v[148:151], v156 offset:1024
	ds_read_b128 v[152:155], v156 offset:2048
	ds_read_b128 v[156:159], v156 offset:3072
	s_add_u32 s26, s26, 0x80000
	s_addc_u32 s27, s27, 0
	s_mov_b32 m0, s43
	v_lshl_add_u64 v[238:239], s[26:27], 0, v[168:169]
	ds_read_b128 v[160:163], v217 offset:32768
	ds_read_b128 v[164:167], v217 offset:33792
	ds_read_b128 v[188:191], v217 offset:34816
	ds_read_b128 v[192:195], v217 offset:35840
	ds_read_b128 v[196:199], v217 offset:36864
	ds_read_b128 v[202:205], v217 offset:37888
	ds_read_b128 v[206:209], v217 offset:38912
	ds_read_b128 v[220:223], v217 offset:39936
	global_load_lds_dwordx4 v[238:239], off
	v_lshl_add_u64 v[238:239], s[26:27], 0, v[172:173]
	s_mov_b32 m0, s44
	s_nop 0
	global_load_lds_dwordx4 v[238:239], off
	s_waitcnt vmcnt(8)
	s_waitcnt lgkmcnt(0)
	s_setprio 1
	s_barrier
	v_mfma_f32_16x16x32_bf16 v[124:127], v[128:131], v[160:163], v[124:127]
	v_mfma_f32_16x16x32_bf16 v[120:123], v[136:139], v[160:163], v[120:123]
	v_mfma_f32_16x16x32_bf16 v[108:111], v[128:131], v[188:191], v[108:111]
	v_mfma_f32_16x16x32_bf16 v[104:107], v[136:139], v[188:191], v[104:107]
	v_mfma_f32_16x16x32_bf16 v[92:95], v[128:131], v[196:199], v[92:95]
	v_mfma_f32_16x16x32_bf16 v[88:91], v[136:139], v[196:199], v[88:91]
	v_mfma_f32_16x16x32_bf16 v[76:79], v[128:131], v[206:209], v[76:79]
	v_mfma_f32_16x16x32_bf16 v[72:75], v[136:139], v[206:209], v[72:75]
	v_mfma_f32_16x16x32_bf16 v[124:127], v[132:135], v[164:167], v[124:127]
	v_mfma_f32_16x16x32_bf16 v[120:123], v[140:143], v[164:167], v[120:123]
	v_mfma_f32_16x16x32_bf16 v[108:111], v[132:135], v[192:195], v[108:111]
	v_mfma_f32_16x16x32_bf16 v[104:107], v[140:143], v[192:195], v[104:107]
	v_mfma_f32_16x16x32_bf16 v[92:95], v[132:135], v[202:205], v[92:95]
	v_mfma_f32_16x16x32_bf16 v[88:91], v[140:143], v[202:205], v[88:91]
	v_mfma_f32_16x16x32_bf16 v[76:79], v[132:135], v[220:223], v[76:79]
	v_mfma_f32_16x16x32_bf16 v[72:75], v[140:143], v[220:223], v[72:75]
	s_setprio 0
	s_setprio 1
	v_mfma_f32_16x16x32_bf16 v[116:119], v[144:147], v[160:163], v[116:119]
	v_mfma_f32_16x16x32_bf16 v[112:115], v[152:155], v[160:163], v[112:115]
	v_mfma_f32_16x16x32_bf16 v[100:103], v[144:147], v[188:191], v[100:103]
	v_mfma_f32_16x16x32_bf16 v[96:99], v[152:155], v[188:191], v[96:99]
	v_mfma_f32_16x16x32_bf16 v[84:87], v[144:147], v[196:199], v[84:87]
	v_mfma_f32_16x16x32_bf16 v[80:83], v[152:155], v[196:199], v[80:83]
	v_mfma_f32_16x16x32_bf16 v[68:71], v[144:147], v[206:209], v[68:71]
	v_mfma_f32_16x16x32_bf16 v[64:67], v[152:155], v[206:209], v[64:67]
	v_mfma_f32_16x16x32_bf16 v[116:119], v[148:151], v[164:167], v[116:119]
	v_mfma_f32_16x16x32_bf16 v[112:115], v[156:159], v[164:167], v[112:115]
	v_mfma_f32_16x16x32_bf16 v[100:103], v[148:151], v[192:195], v[100:103]
	v_mfma_f32_16x16x32_bf16 v[96:99], v[156:159], v[192:195], v[96:99]
	v_mfma_f32_16x16x32_bf16 v[84:87], v[148:151], v[202:205], v[84:87]
	v_mfma_f32_16x16x32_bf16 v[80:83], v[156:159], v[202:205], v[80:83]
	v_mfma_f32_16x16x32_bf16 v[68:71], v[148:151], v[220:223], v[68:71]
	v_mfma_f32_16x16x32_bf16 v[64:67], v[156:159], v[220:223], v[64:67]
	s_barrier
; #define PG8_STAGE(bufoff, gbase, voff) do { _Pragma("unroll") for (int _i = 0; _i < 2; ++_i) \
;         __builtin_amdgcn_global_load_lds((const unsigned*)((const char*)(gbase) + (voff)[_i]), (PG8_LAS unsigned*)(lds + (bufoff) + ldsw + _i * 8192), 16, 0, 0); } while (0)
; #define PG8_LDA(dst, b, h) do { _Pragma("unroll") for (int m = 0; m < 4; ++m) _Pragma("unroll") for (int k = 0; k < 2; ++k) dst[m][k] = *(const PG8_LAS bf16x8*)(lds + PG8_SA(b, h) + aoff + m * 2048 + k * 1024); } while (0)
; #define PG8_MMA(ai, bj, At, Bt) do { __builtin_amdgcn_s_setprio(1); _Pragma("unroll") for (int m = 0; m < 4; ++m) _Pragma("unroll") for (int n = 0; n < 2; ++n) _Pragma("unroll") for (int k = 0; k < 2; ++k) \
;         acc[ai][bj][m][n] = __builtin_amdgcn_mfma_f32_16x16x32_bf16(Bt[n][k], At[m][k], acc[ai][bj][m][n], 0, 0, 0); __builtin_amdgcn_s_setprio(0); } while (0)
; #define PG8_WAIT_V(n) asm volatile("s_waitcnt vmcnt(" #n ")" ::: "memory")
; #define PG8_WAIT_L(n) asm volatile("s_waitcnt lgkmcnt(" #n ")" ::: "memory")
; #define PG8_BAR __builtin_amdgcn_s_barrier()
; #define PG8_SCHED __builtin_amdgcn_sched_barrier(0)
; template <class Epi, class Sched, bool ALIGN_EPI = false, bool SP2 = false, bool DUAL = false>
; __device__ __forceinline__ void gemm_phase(PG8_LAS unsigned char* lds, const Gemm g, const Sched& S, const Epi& E) {
;     ...
;             PG8_LDA(At, 1, 1); PG8_STAGE(PG8_SB(1, 0), b3, voffB); PG8_STAGE(PG8_SB(1, 1), b3 + hstep, voffB); PG8_STAGE(PG8_SA(1, 0), a3, voffA);
;             PG8_WAIT_V(8); PG8_WAIT_L(0); PG8_BAR; PG8_MMA(1, 0, At, B0); PG8_MMA(1, 1, At, B1); PG8_BAR; PG8_SCHED;
	s_setprio 0
	s_add_i32 s26, s66, s34
	v_lshl_add_u64 v[228:229], v[228:229], 0, s[12:13]
	s_mov_b32 m0, s26
	ds_read_b128 v[160:163], v217 offset:49152
	ds_read_b128 v[164:167], v217 offset:50176
	ds_read_b128 v[188:191], v217 offset:51200
	ds_read_b128 v[192:195], v217 offset:52224
	ds_read_b128 v[196:199], v217 offset:53248
	ds_read_b128 v[202:205], v217 offset:54272
	ds_read_b128 v[206:209], v217 offset:55296
	ds_read_b128 v[220:223], v217 offset:56320
	global_load_lds_dwordx4 v[228:229], off
	s_add_i32 m0, s26, 0x2000
	s_add_u32 s14, s14, 0x80080
	v_lshl_add_u64 v[228:229], v[232:233], 0, s[12:13]
	s_addc_u32 s15, s15, 0
	s_add_i32 s26, s67, s34
	global_load_lds_dwordx4 v[228:229], off
	v_lshl_add_u64 v[228:229], s[14:15], 0, v[170:171]
	s_mov_b32 m0, s26
	s_nop 0
	global_load_lds_dwordx4 v[228:229], off
	v_lshl_add_u64 v[228:229], s[14:15], 0, v[174:175]
	s_add_i32 m0, s26, 0x2000
	s_nop 0
	global_load_lds_dwordx4 v[228:229], off
	v_lshl_add_u64 v[228:229], v[234:235], 0, s[12:13]
	s_mov_b32 m0, s47
	s_nop 0
	global_load_lds_dwordx4 v[228:229], off
	v_lshl_add_u64 v[228:229], v[236:237], 0, s[12:13]
	s_mov_b32 m0, s48
	s_nop 0
	global_load_lds_dwordx4 v[228:229], off
	s_waitcnt vmcnt(8)
	s_waitcnt lgkmcnt(0)
	s_setprio 1
	s_barrier
	v_mfma_f32_16x16x32_bf16 v[60:63], v[128:131], v[160:163], v[60:63]
	v_mfma_f32_16x16x32_bf16 v[56:59], v[136:139], v[160:163], v[56:59]
	v_mfma_f32_16x16x32_bf16 v[44:47], v[128:131], v[188:191], v[44:47]
	v_mfma_f32_16x16x32_bf16 v[40:43], v[136:139], v[188:191], v[40:43]
	v_mfma_f32_16x16x32_bf16 v[28:31], v[128:131], v[196:199], v[28:31]
	v_mfma_f32_16x16x32_bf16 v[24:27], v[136:139], v[196:199], v[24:27]
	v_mfma_f32_16x16x32_bf16 v[12:15], v[128:131], v[206:209], v[12:15]
	v_mfma_f32_16x16x32_bf16 v[8:11], v[136:139], v[206:209], v[8:11]
	v_mfma_f32_16x16x32_bf16 v[60:63], v[132:135], v[164:167], v[60:63]
	v_mfma_f32_16x16x32_bf16 v[56:59], v[140:143], v[164:167], v[56:59]
	v_mfma_f32_16x16x32_bf16 v[44:47], v[132:135], v[192:195], v[44:47]
	v_mfma_f32_16x16x32_bf16 v[40:43], v[140:143], v[192:195], v[40:43]
	v_mfma_f32_16x16x32_bf16 v[28:31], v[132:135], v[202:205], v[28:31]
	v_mfma_f32_16x16x32_bf16 v[24:27], v[140:143], v[202:205], v[24:27]
	v_mfma_f32_16x16x32_bf16 v[12:15], v[132:135], v[220:223], v[12:15]
	v_mfma_f32_16x16x32_bf16 v[8:11], v[140:143], v[220:223], v[8:11]
	s_setprio 0
	s_setprio 1
	v_mfma_f32_16x16x32_bf16 v[52:55], v[144:147], v[160:163], v[52:55]
	v_mfma_f32_16x16x32_bf16 v[48:51], v[152:155], v[160:163], v[48:51]
	v_mfma_f32_16x16x32_bf16 v[36:39], v[144:147], v[188:191], v[36:39]
	v_mfma_f32_16x16x32_bf16 v[32:35], v[152:155], v[188:191], v[32:35]
	v_mfma_f32_16x16x32_bf16 v[20:23], v[144:147], v[196:199], v[20:23]
	v_mfma_f32_16x16x32_bf16 v[16:19], v[152:155], v[196:199], v[16:19]
	v_mfma_f32_16x16x32_bf16 v[4:7], v[144:147], v[206:209], v[4:7]
	v_mfma_f32_16x16x32_bf16 v[0:3], v[152:155], v[206:209], v[0:3]
	v_mfma_f32_16x16x32_bf16 v[52:55], v[148:151], v[164:167], v[52:55]
	v_mfma_f32_16x16x32_bf16 v[48:51], v[156:159], v[164:167], v[48:51]
	v_mfma_f32_16x16x32_bf16 v[36:39], v[148:151], v[192:195], v[36:39]
	v_mfma_f32_16x16x32_bf16 v[32:35], v[156:159], v[192:195], v[32:35]
	v_mfma_f32_16x16x32_bf16 v[20:23], v[148:151], v[202:205], v[20:23]
	v_mfma_f32_16x16x32_bf16 v[16:19], v[156:159], v[202:205], v[16:19]
	v_mfma_f32_16x16x32_bf16 v[4:7], v[148:151], v[220:223], v[4:7]
	v_mfma_f32_16x16x32_bf16 v[0:3], v[156:159], v[220:223], v[0:3]
	s_barrier
	s_setprio 0
	s_add_i32 s65, s65, 2
	s_add_u32 s40, s40, 0x100
	s_addc_u32 s41, s41, 0
	s_add_u32 s63, s63, 0x100
	s_addc_u32 s64, s64, 0

; #define PG8_STAGE(bufoff, gbase, voff) do { _Pragma("unroll") for (int _i = 0; _i < 2; ++_i) \
;         __builtin_amdgcn_global_load_lds((const unsigned*)((const char*)(gbase) + (voff)[_i]), (PG8_LAS unsigned*)(lds + (bufoff) + ldsw + _i * 8192), 16, 0, 0); } while (0)
; #define PG8_LDA(dst, b, h) do { _Pragma("unroll") for (int m = 0; m < 4; ++m) _Pragma("unroll") for (int k = 0; k < 2; ++k) dst[m][k] = *(const PG8_LAS bf16x8*)(lds + PG8_SA(b, h) + aoff + m * 2048 + k * 1024); } while (0)
; #define PG8_LDB(dst, b, h) do { _Pragma("unroll") for (int n = 0; n < 2; ++n) _Pragma("unroll") for (int k = 0; k < 2; ++k) dst[n][k] = *(const PG8_LAS bf16x8*)(lds + PG8_SB(b, h) + boff + n * 2048 + k * 1024); } while (0)
; #define PG8_MMA(ai, bj, At, Bt) do { __builtin_amdgcn_s_setprio(1); _Pragma("unroll") for (int m = 0; m < 4; ++m) _Pragma("unroll") for (int n = 0; n < 2; ++n) _Pragma("unroll") for (int k = 0; k < 2; ++k) \
;         acc[ai][bj][m][n] = __builtin_amdgcn_mfma_f32_16x16x32_bf16(Bt[n][k], At[m][k], acc[ai][bj][m][n], 0, 0, 0); __builtin_amdgcn_s_setprio(0); } while (0)
; #define PG8_WAIT_V(n) asm volatile("s_waitcnt vmcnt(" #n ")" ::: "memory")
; #define PG8_BAR __builtin_amdgcn_s_barrier()
; template <class Epi, class Sched, bool ALIGN_EPI = false, bool SP2 = false, bool DUAL = false>
; __device__ __forceinline__ void gemm_phase(PG8_LAS unsigned char* lds, const Gemm g, const Sched& S, const Epi& E) {
;     ...
;         for (int t = 0; t < nt; t += 2) {
;             const bool last = (t == nt - 2);
;             const char* a1 = cA + (size_t)(t + 1) * kstep;
;             const char* a2 = last ? nA : cA + (size_t)(t + 2) * kstep; const char* b2 = last ? nB : cB + (size_t)(t + 2) * kstep;
;             const char* a3 = a2 + kstep; const char* b3 = b2 + kstep;
;             if (last && has_next) S.a_ready(nxt);
;             if constexpr (SP2) {
;             PG8_LDB(B0, 0, 0); PG8_LDB(B1, 0, 1); PG8_SCHED; PG8_LDA(At, 0, 0); PG8_STAGE(PG8_SA(1, 1), a1 + hstep, voffA);
;             PG8_WAIT_V(8); PG8_WAIT_L(0); PG8_BAR; PG8_MMA(0, 0, At, B0); PG8_MMA(0, 1, At, B1); PG8_BAR; PG8_SCHED;
;             PG8_LDA(At, 0, 1); PG8_STAGE(PG8_SB(0, 0), b2, voffB); PG8_STAGE(PG8_SB(0, 1), b2 + hstep, voffB); PG8_STAGE(PG8_SA(0, 0), a2, voffA);
;             PG8_WAIT_V(8); PG8_WAIT_L(0); PG8_BAR; PG8_MMA(1, 0, At, B0); PG8_MMA(1, 1, At, B1); PG8_BAR; PG8_SCHED;
.LBB0_1192:
	s_add_u32 s24, s24, 0x160080
	s_addc_u32 s25, s25, 0
	s_add_u32 s46, s14, 0x100
	s_addc_u32 s47, s15, 0
	s_mov_b32 s48, -2
	s_add_u32 s14, s24, 0xffea0080
	s_addc_u32 s15, s25, -1
	s_cmpk_eq_i32 s48, 0x54
	s_cselect_b32 s27, s5, s15
	s_cselect_b32 s26, s4, s14
	s_cselect_b32 s15, s23, s47
	s_cselect_b32 s14, s22, s46
	s_waitcnt vmcnt(8)
	s_waitcnt lgkmcnt(0)
	s_setprio 1
	s_barrier
	v_mfma_f32_16x16x32_bf16 v[124:127], v[128:131], v[160:163], 0
	v_mfma_f32_16x16x32_bf16 v[120:123], v[136:139], v[160:163], 0
	v_mfma_f32_16x16x32_bf16 v[112:115], v[128:131], v[186:189], 0
	v_mfma_f32_16x16x32_bf16 v[104:107], v[136:139], v[186:189], 0
	v_mfma_f32_16x16x32_bf16 v[96:99], v[128:131], v[204:207], 0
	v_mfma_f32_16x16x32_bf16 v[88:91], v[136:139], v[204:207], 0
	v_mfma_f32_16x16x32_bf16 v[80:83], v[128:131], v[212:215], 0
	v_mfma_f32_16x16x32_bf16 v[72:75], v[136:139], v[212:215], 0
	v_mfma_f32_16x16x32_bf16 v[124:127], v[132:135], v[182:185], v[124:127]
	v_mfma_f32_16x16x32_bf16 v[120:123], v[140:143], v[182:185], v[120:123]
	v_mfma_f32_16x16x32_bf16 v[112:115], v[132:135], v[190:193], v[112:115]
	v_mfma_f32_16x16x32_bf16 v[104:107], v[140:143], v[190:193], v[104:107]
	v_mfma_f32_16x16x32_bf16 v[96:99], v[132:135], v[208:211], v[96:99]
	v_mfma_f32_16x16x32_bf16 v[88:91], v[140:143], v[208:211], v[88:91]
	v_mfma_f32_16x16x32_bf16 v[80:83], v[132:135], v[216:219], v[80:83]
	v_mfma_f32_16x16x32_bf16 v[72:75], v[140:143], v[216:219], v[72:75]
	s_setprio 0
	s_setprio 1
	v_mfma_f32_16x16x32_bf16 v[116:119], v[144:147], v[160:163], 0
	v_mfma_f32_16x16x32_bf16 v[108:111], v[152:155], v[160:163], 0
	v_mfma_f32_16x16x32_bf16 v[100:103], v[144:147], v[186:189], 0
	v_mfma_f32_16x16x32_bf16 v[92:95], v[152:155], v[186:189], 0
	v_mfma_f32_16x16x32_bf16 v[84:87], v[144:147], v[204:207], 0
	v_mfma_f32_16x16x32_bf16 v[76:79], v[152:155], v[204:207], 0
	v_mfma_f32_16x16x32_bf16 v[68:71], v[144:147], v[212:215], 0
	v_mfma_f32_16x16x32_bf16 v[64:67], v[152:155], v[212:215], 0
	v_mfma_f32_16x16x32_bf16 v[116:119], v[148:151], v[182:185], v[116:119]
	v_mfma_f32_16x16x32_bf16 v[108:111], v[156:159], v[182:185], v[108:111]
	v_mfma_f32_16x16x32_bf16 v[100:103], v[148:151], v[190:193], v[100:103]
	v_mfma_f32_16x16x32_bf16 v[92:95], v[156:159], v[190:193], v[92:95]
	v_mfma_f32_16x16x32_bf16 v[84:87], v[148:151], v[208:211], v[84:87]
	v_mfma_f32_16x16x32_bf16 v[76:79], v[156:159], v[208:211], v[76:79]
	v_mfma_f32_16x16x32_bf16 v[68:71], v[148:151], v[216:219], v[68:71]
	v_mfma_f32_16x16x32_bf16 v[64:67], v[156:159], v[216:219], v[64:67]
	s_barrier
	s_setprio 0
	v_lshl_add_u64 v[220:221], s[24:25], 0, v[172:173]
	s_add_i32 m0, s31, 0xc000
	s_nop 0
	global_load_lds_dwordx4 v[220:221], off
	v_lshl_add_u64 v[220:221], s[24:25], 0, v[174:175]
	s_add_i32 m0, s31, 0xe000
	s_nop 0
	global_load_lds_dwordx4 v[220:221], off
	s_add_i32 s49, s40, s30
	v_lshl_add_u64 v[220:221], s[14:15], 0, v[166:167]
	s_mov_b32 m0, s49
	ds_read_b128 v[160:163], v203 offset:16384
	ds_read_b128 v[182:185], v203 offset:17408
	ds_read_b128 v[186:189], v203 offset:18432
	ds_read_b128 v[190:193], v203 offset:19456
	ds_read_b128 v[204:207], v203 offset:20480
	ds_read_b128 v[208:211], v203 offset:21504
	ds_read_b128 v[212:215], v203 offset:22528
	ds_read_b128 v[216:219], v203 offset:23552
	global_load_lds_dwordx4 v[220:221], off
	s_add_i32 m0, s49, 0x2000
	s_add_u32 s50, s14, 0x160000
	v_lshl_add_u64 v[222:223], s[14:15], 0, v[170:171]
	s_addc_u32 s51, s15, 0
	s_add_i32 s49, s41, s30
	global_load_lds_dwordx4 v[222:223], off
	v_lshl_add_u64 v[224:225], s[50:51], 0, v[166:167]
	s_mov_b32 m0, s49
	v_lshl_add_u64 v[226:227], s[26:27], 0, v[168:169]
	global_load_lds_dwordx4 v[224:225], off
	v_lshl_add_u64 v[224:225], s[50:51], 0, v[170:171]
	s_add_i32 m0, s49, 0x2000
	s_nop 0
	global_load_lds_dwordx4 v[224:225], off
	v_lshl_add_u64 v[224:225], s[26:27], 0, v[164:165]
	s_mov_b32 m0, s31
	s_nop 0
	global_load_lds_dwordx4 v[224:225], off
	s_mov_b32 m0, s33
	s_nop 0
	global_load_lds_dwordx4 v[226:227], off
	s_waitcnt vmcnt(8)
	s_waitcnt lgkmcnt(0)
	s_setprio 1
	s_barrier
	v_mfma_f32_16x16x32_bf16 v[60:63], v[128:131], v[160:163], 0
	v_mfma_f32_16x16x32_bf16 v[56:59], v[136:139], v[160:163], 0
	v_mfma_f32_16x16x32_bf16 v[48:51], v[128:131], v[186:189], 0
	v_mfma_f32_16x16x32_bf16 v[40:43], v[136:139], v[186:189], 0
	v_mfma_f32_16x16x32_bf16 v[32:35], v[128:131], v[204:207], 0
	v_mfma_f32_16x16x32_bf16 v[24:27], v[136:139], v[204:207], 0
	v_mfma_f32_16x16x32_bf16 v[16:19], v[128:131], v[212:215], 0
	v_mfma_f32_16x16x32_bf16 v[8:11], v[136:139], v[212:215], 0
	v_mfma_f32_16x16x32_bf16 v[60:63], v[132:135], v[182:185], v[60:63]
	v_mfma_f32_16x16x32_bf16 v[56:59], v[140:143], v[182:185], v[56:59]
	v_mfma_f32_16x16x32_bf16 v[48:51], v[132:135], v[190:193], v[48:51]
	v_mfma_f32_16x16x32_bf16 v[40:43], v[140:143], v[190:193], v[40:43]
	v_mfma_f32_16x16x32_bf16 v[32:35], v[132:135], v[208:211], v[32:35]
	v_mfma_f32_16x16x32_bf16 v[24:27], v[140:143], v[208:211], v[24:27]
	v_mfma_f32_16x16x32_bf16 v[16:19], v[132:135], v[216:219], v[16:19]
	v_mfma_f32_16x16x32_bf16 v[8:11], v[140:143], v[216:219], v[8:11]
	s_setprio 0
	s_setprio 1
	v_mfma_f32_16x16x32_bf16 v[52:55], v[144:147], v[160:163], 0
	v_mfma_f32_16x16x32_bf16 v[44:47], v[152:155], v[160:163], 0
	v_mfma_f32_16x16x32_bf16 v[36:39], v[144:147], v[186:189], 0
	v_mfma_f32_16x16x32_bf16 v[28:31], v[152:155], v[186:189], 0
	v_mfma_f32_16x16x32_bf16 v[20:23], v[144:147], v[204:207], 0
	v_mfma_f32_16x16x32_bf16 v[12:15], v[152:155], v[204:207], 0
	v_mfma_f32_16x16x32_bf16 v[4:7], v[144:147], v[212:215], 0
	v_mfma_f32_16x16x32_bf16 v[0:3], v[152:155], v[212:215], 0
	v_mfma_f32_16x16x32_bf16 v[52:55], v[148:151], v[182:185], v[52:55]
	v_mfma_f32_16x16x32_bf16 v[44:47], v[156:159], v[182:185], v[44:47]
	v_mfma_f32_16x16x32_bf16 v[36:39], v[148:151], v[190:193], v[36:39]
	v_mfma_f32_16x16x32_bf16 v[28:31], v[156:159], v[190:193], v[28:31]
	v_mfma_f32_16x16x32_bf16 v[20:23], v[148:151], v[208:211], v[20:23]
	v_mfma_f32_16x16x32_bf16 v[12:15], v[156:159], v[208:211], v[12:15]
	v_mfma_f32_16x16x32_bf16 v[4:7], v[148:151], v[216:219], v[4:7]
	v_mfma_f32_16x16x32_bf16 v[0:3], v[156:159], v[216:219], v[0:3]
	s_barrier
; #define PG8_STAGE(bufoff, gbase, voff) do { _Pragma("unroll") for (int _i = 0; _i < 2; ++_i) \
;         __builtin_amdgcn_global_load_lds((const unsigned*)((const char*)(gbase) + (voff)[_i]), (PG8_LAS unsigned*)(lds + (bufoff) + ldsw + _i * 8192), 16, 0, 0); } while (0)
; #define PG8_LDA(dst, b, h) do { _Pragma("unroll") for (int m = 0; m < 4; ++m) _Pragma("unroll") for (int k = 0; k < 2; ++k) dst[m][k] = *(const PG8_LAS bf16x8*)(lds + PG8_SA(b, h) + aoff + m * 2048 + k * 1024); } while (0)
; #define PG8_LDB(dst, b, h) do { _Pragma("unroll") for (int n = 0; n < 2; ++n) _Pragma("unroll") for (int k = 0; k < 2; ++k) dst[n][k] = *(const PG8_LAS bf16x8*)(lds + PG8_SB(b, h) + boff + n * 2048 + k * 1024); } while (0)
; #define PG8_MMA(ai, bj, At, Bt) do { __builtin_amdgcn_s_setprio(1); _Pragma("unroll") for (int m = 0; m < 4; ++m) _Pragma("unroll") for (int n = 0; n < 2; ++n) _Pragma("unroll") for (int k = 0; k < 2; ++k) \
;         acc[ai][bj][m][n] = __builtin_amdgcn_mfma_f32_16x16x32_bf16(Bt[n][k], At[m][k], acc[ai][bj][m][n], 0, 0, 0); __builtin_amdgcn_s_setprio(0); } while (0)
; #define PG8_WAIT_V(n) asm volatile("s_waitcnt vmcnt(" #n ")" ::: "memory")
; #define PG8_WAIT_L(n) asm volatile("s_waitcnt lgkmcnt(" #n ")" ::: "memory")
; #define PG8_BAR __builtin_amdgcn_s_barrier()
; #define PG8_SCHED __builtin_amdgcn_sched_barrier(0)
; template <class Epi, class Sched, bool ALIGN_EPI = false, bool SP2 = false, bool DUAL = false>
; __device__ __forceinline__ void gemm_phase(PG8_LAS unsigned char* lds, const Gemm g, const Sched& S, const Epi& E) {
;     ...
;             PG8_LDB(B0, 1, 0); PG8_LDB(B1, 1, 1); PG8_SCHED; PG8_LDA(At, 1, 0); PG8_STAGE(PG8_SA(0, 1), a2 + hstep, voffA);
;             PG8_WAIT_V(8); PG8_WAIT_L(0); PG8_BAR; PG8_MMA(0, 0, At, B0); PG8_MMA(0, 1, At, B1); PG8_BAR; PG8_SCHED;
	s_setprio 0
	s_add_i32 s49, 0, 0x18000
	s_add_i32 s50, 0, 0x1c000
	v_add_u32_e32 v140, s49, v198
	v_add_u32_e32 v156, s50, v198
	ds_read_b128 v[128:131], v140
	ds_read_b128 v[132:135], v140 offset:1024
	ds_read_b128 v[136:139], v140 offset:2048
	ds_read_b128 v[140:143], v140 offset:3072
	ds_read_b128 v[144:147], v156
	ds_read_b128 v[148:151], v156 offset:1024
	ds_read_b128 v[152:155], v156 offset:2048
	ds_read_b128 v[156:159], v156 offset:3072
	s_add_u32 s26, s26, 0x160000
	s_addc_u32 s27, s27, 0
	s_mov_b32 m0, s34
	v_lshl_add_u64 v[228:229], s[26:27], 0, v[164:165]
	ds_read_b128 v[160:163], v203 offset:32768
	ds_read_b128 v[182:185], v203 offset:33792
	ds_read_b128 v[186:189], v203 offset:34816
	ds_read_b128 v[190:193], v203 offset:35840
	ds_read_b128 v[204:207], v203 offset:36864
	ds_read_b128 v[208:211], v203 offset:37888
	ds_read_b128 v[212:215], v203 offset:38912
	ds_read_b128 v[216:219], v203 offset:39936
	global_load_lds_dwordx4 v[228:229], off
	v_lshl_add_u64 v[228:229], s[26:27], 0, v[168:169]
	s_mov_b32 m0, s35
	s_nop 0
	global_load_lds_dwordx4 v[228:229], off
	s_waitcnt vmcnt(8)
	s_waitcnt lgkmcnt(0)
	s_setprio 1
	s_barrier
	v_mfma_f32_16x16x32_bf16 v[124:127], v[128:131], v[160:163], v[124:127]
	v_mfma_f32_16x16x32_bf16 v[120:123], v[136:139], v[160:163], v[120:123]
	v_mfma_f32_16x16x32_bf16 v[112:115], v[128:131], v[186:189], v[112:115]
	v_mfma_f32_16x16x32_bf16 v[104:107], v[136:139], v[186:189], v[104:107]
	v_mfma_f32_16x16x32_bf16 v[96:99], v[128:131], v[204:207], v[96:99]
	v_mfma_f32_16x16x32_bf16 v[88:91], v[136:139], v[204:207], v[88:91]
	v_mfma_f32_16x16x32_bf16 v[80:83], v[128:131], v[212:215], v[80:83]
	v_mfma_f32_16x16x32_bf16 v[72:75], v[136:139], v[212:215], v[72:75]
	v_mfma_f32_16x16x32_bf16 v[124:127], v[132:135], v[182:185], v[124:127]
	v_mfma_f32_16x16x32_bf16 v[120:123], v[140:143], v[182:185], v[120:123]
	v_mfma_f32_16x16x32_bf16 v[112:115], v[132:135], v[190:193], v[112:115]
	v_mfma_f32_16x16x32_bf16 v[104:107], v[140:143], v[190:193], v[104:107]
	v_mfma_f32_16x16x32_bf16 v[96:99], v[132:135], v[208:211], v[96:99]
	v_mfma_f32_16x16x32_bf16 v[88:91], v[140:143], v[208:211], v[88:91]
	v_mfma_f32_16x16x32_bf16 v[80:83], v[132:135], v[216:219], v[80:83]
	v_mfma_f32_16x16x32_bf16 v[72:75], v[140:143], v[216:219], v[72:75]
	s_setprio 0
	s_setprio 1
	v_mfma_f32_16x16x32_bf16 v[116:119], v[144:147], v[160:163], v[116:119]
	v_mfma_f32_16x16x32_bf16 v[108:111], v[152:155], v[160:163], v[108:111]
	v_mfma_f32_16x16x32_bf16 v[100:103], v[144:147], v[186:189], v[100:103]
	v_mfma_f32_16x16x32_bf16 v[92:95], v[152:155], v[186:189], v[92:95]
	v_mfma_f32_16x16x32_bf16 v[84:87], v[144:147], v[204:207], v[84:87]
	v_mfma_f32_16x16x32_bf16 v[76:79], v[152:155], v[204:207], v[76:79]
	v_mfma_f32_16x16x32_bf16 v[68:71], v[144:147], v[212:215], v[68:71]
	v_mfma_f32_16x16x32_bf16 v[64:67], v[152:155], v[212:215], v[64:67]
	v_mfma_f32_16x16x32_bf16 v[116:119], v[148:151], v[182:185], v[116:119]
	v_mfma_f32_16x16x32_bf16 v[108:111], v[156:159], v[182:185], v[108:111]
	v_mfma_f32_16x16x32_bf16 v[100:103], v[148:151], v[190:193], v[100:103]
	v_mfma_f32_16x16x32_bf16 v[92:95], v[156:159], v[190:193], v[92:95]
	v_mfma_f32_16x16x32_bf16 v[84:87], v[148:151], v[208:211], v[84:87]
	v_mfma_f32_16x16x32_bf16 v[76:79], v[156:159], v[208:211], v[76:79]
	v_mfma_f32_16x16x32_bf16 v[68:71], v[148:151], v[216:219], v[68:71]
	v_mfma_f32_16x16x32_bf16 v[64:67], v[156:159], v[216:219], v[64:67]
	s_barrier
; #define PG8_STAGE(bufoff, gbase, voff) do { _Pragma("unroll") for (int _i = 0; _i < 2; ++_i) \
;         __builtin_amdgcn_global_load_lds((const unsigned*)((const char*)(gbase) + (voff)[_i]), (PG8_LAS unsigned*)(lds + (bufoff) + ldsw + _i * 8192), 16, 0, 0); } while (0)
; #define PG8_LDA(dst, b, h) do { _Pragma("unroll") for (int m = 0; m < 4; ++m) _Pragma("unroll") for (int k = 0; k < 2; ++k) dst[m][k] = *(const PG8_LAS bf16x8*)(lds + PG8_SA(b, h) + aoff + m * 2048 + k * 1024); } while (0)
; #define PG8_MMA(ai, bj, At, Bt) do { __builtin_amdgcn_s_setprio(1); _Pragma("unroll") for (int m = 0; m < 4; ++m) _Pragma("unroll") for (int n = 0; n < 2; ++n) _Pragma("unroll") for (int k = 0; k < 2; ++k) \
;         acc[ai][bj][m][n] = __builtin_amdgcn_mfma_f32_16x16x32_bf16(Bt[n][k], At[m][k], acc[ai][bj][m][n], 0, 0, 0); __builtin_amdgcn_s_setprio(0); } while (0)
; #define PG8_WAIT_V(n) asm volatile("s_waitcnt vmcnt(" #n ")" ::: "memory")
; #define PG8_WAIT_L(n) asm volatile("s_waitcnt lgkmcnt(" #n ")" ::: "memory")
; #define PG8_BAR __builtin_amdgcn_s_barrier()
; #define PG8_SCHED __builtin_amdgcn_sched_barrier(0)
; template <class Epi, class Sched, bool ALIGN_EPI = false, bool SP2 = false, bool DUAL = false>
; __device__ __forceinline__ void gemm_phase(PG8_LAS unsigned char* lds, const Gemm g, const Sched& S, const Epi& E) {
;     ...
;             PG8_LDA(At, 1, 1); PG8_STAGE(PG8_SB(1, 0), b3, voffB); PG8_STAGE(PG8_SB(1, 1), b3 + hstep, voffB); PG8_STAGE(PG8_SA(1, 0), a3, voffA);
;             PG8_WAIT_V(8); PG8_WAIT_L(0); PG8_BAR; PG8_MMA(1, 0, At, B0); PG8_MMA(1, 1, At, B1); PG8_BAR; PG8_SCHED;
	s_setprio 0
	s_add_i32 s26, s49, s30
	v_lshl_add_u64 v[220:221], v[220:221], 0, s[18:19]
	s_mov_b32 m0, s26
	ds_read_b128 v[160:163], v203 offset:49152
	ds_read_b128 v[182:185], v203 offset:50176
	ds_read_b128 v[186:189], v203 offset:51200
	ds_read_b128 v[190:193], v203 offset:52224
	ds_read_b128 v[204:207], v203 offset:53248
	ds_read_b128 v[208:211], v203 offset:54272
	ds_read_b128 v[212:215], v203 offset:55296
	ds_read_b128 v[216:219], v203 offset:56320
	global_load_lds_dwordx4 v[220:221], off
	s_add_i32 m0, s26, 0x2000
	s_add_u32 s14, s14, 0x160080
	v_lshl_add_u64 v[220:221], v[222:223], 0, s[18:19]
	s_addc_u32 s15, s15, 0
	s_add_i32 s26, s50, s30
	global_load_lds_dwordx4 v[220:221], off
	v_lshl_add_u64 v[220:221], s[14:15], 0, v[166:167]
	s_mov_b32 m0, s26
	s_nop 0
	global_load_lds_dwordx4 v[220:221], off
	v_lshl_add_u64 v[220:221], s[14:15], 0, v[170:171]
	s_add_i32 m0, s26, 0x2000
	s_nop 0
	global_load_lds_dwordx4 v[220:221], off
	v_lshl_add_u64 v[220:221], v[224:225], 0, s[18:19]
	s_mov_b32 m0, s37
	s_nop 0
	global_load_lds_dwordx4 v[220:221], off
	v_lshl_add_u64 v[220:221], v[226:227], 0, s[18:19]
	s_mov_b32 m0, s38
	s_nop 0
	global_load_lds_dwordx4 v[220:221], off
	s_waitcnt vmcnt(8)
	s_waitcnt lgkmcnt(0)
	s_setprio 1
	s_barrier
	v_mfma_f32_16x16x32_bf16 v[60:63], v[128:131], v[160:163], v[60:63]
	v_mfma_f32_16x16x32_bf16 v[56:59], v[136:139], v[160:163], v[56:59]
	v_mfma_f32_16x16x32_bf16 v[48:51], v[128:131], v[186:189], v[48:51]
	v_mfma_f32_16x16x32_bf16 v[40:43], v[136:139], v[186:189], v[40:43]
	v_mfma_f32_16x16x32_bf16 v[32:35], v[128:131], v[204:207], v[32:35]
	v_mfma_f32_16x16x32_bf16 v[24:27], v[136:139], v[204:207], v[24:27]
	v_mfma_f32_16x16x32_bf16 v[16:19], v[128:131], v[212:215], v[16:19]
	v_mfma_f32_16x16x32_bf16 v[8:11], v[136:139], v[212:215], v[8:11]
	v_mfma_f32_16x16x32_bf16 v[60:63], v[132:135], v[182:185], v[60:63]
	v_mfma_f32_16x16x32_bf16 v[56:59], v[140:143], v[182:185], v[56:59]
	v_mfma_f32_16x16x32_bf16 v[48:51], v[132:135], v[190:193], v[48:51]
	v_mfma_f32_16x16x32_bf16 v[40:43], v[140:143], v[190:193], v[40:43]
	v_mfma_f32_16x16x32_bf16 v[32:35], v[132:135], v[208:211], v[32:35]
	v_mfma_f32_16x16x32_bf16 v[24:27], v[140:143], v[208:211], v[24:27]
	v_mfma_f32_16x16x32_bf16 v[16:19], v[132:135], v[216:219], v[16:19]
	v_mfma_f32_16x16x32_bf16 v[8:11], v[140:143], v[216:219], v[8:11]
	s_setprio 0
	s_setprio 1
	v_mfma_f32_16x16x32_bf16 v[52:55], v[144:147], v[160:163], v[52:55]
	v_mfma_f32_16x16x32_bf16 v[44:47], v[152:155], v[160:163], v[44:47]
	v_mfma_f32_16x16x32_bf16 v[36:39], v[144:147], v[186:189], v[36:39]
	v_mfma_f32_16x16x32_bf16 v[28:31], v[152:155], v[186:189], v[28:31]
	v_mfma_f32_16x16x32_bf16 v[20:23], v[144:147], v[204:207], v[20:23]
	v_mfma_f32_16x16x32_bf16 v[12:15], v[152:155], v[204:207], v[12:15]
	v_mfma_f32_16x16x32_bf16 v[4:7], v[144:147], v[212:215], v[4:7]
	v_mfma_f32_16x16x32_bf16 v[0:3], v[152:155], v[212:215], v[0:3]
	v_mfma_f32_16x16x32_bf16 v[52:55], v[148:151], v[182:185], v[52:55]
	v_mfma_f32_16x16x32_bf16 v[44:47], v[156:159], v[182:185], v[44:47]
	v_mfma_f32_16x16x32_bf16 v[36:39], v[148:151], v[190:193], v[36:39]
	v_mfma_f32_16x16x32_bf16 v[28:31], v[156:159], v[190:193], v[28:31]
	v_mfma_f32_16x16x32_bf16 v[20:23], v[148:151], v[208:211], v[20:23]
	v_mfma_f32_16x16x32_bf16 v[12:15], v[156:159], v[208:211], v[12:15]
	v_mfma_f32_16x16x32_bf16 v[4:7], v[148:151], v[216:219], v[4:7]
	v_mfma_f32_16x16x32_bf16 v[0:3], v[156:159], v[216:219], v[0:3]
	s_barrier
	s_setprio 0
	s_add_i32 s48, s48, 2
	s_add_u32 s24, s24, 0x100
	s_addc_u32 s25, s25, 0
	s_add_u32 s46, s46, 0x100
	s_addc_u32 s47, s47, 0
